# up-proj (phase D) epilogue rewritten by hand: all gate/merged loads ahead of stores, 16B accesses via v_permlane16_swap
# speedup vs baseline: 1.0499x; 1.0167x over previous
; DI void phaseD(const Params& p0, const Slot sl, int layer, unsigned char* lds) {
;     ...
;   for (int it = 0; tile_order(sl, it, 4, mt, nt); ++it) {
; #pragma unroll 1
;     for (int which = 0; which < 2; ++which) {
;       const bf16_t* Wg = (which ? p.wupb_t() : p.wupa_t()) + ((long)nt * 256) * 512;
;       const bf16_t* Yg = (which ? p.nz() : p.sbz()) + (long)mt * 256 * 512;
;       const bf16_t* Gg = which ? p.gb() : p.ga();
;       int mt2 = mt, nt2 = nt; bool more = true;
;       if (which) more = tile_order(sl, it + 1, 4, mt2, nt2);
;       const bf16_t* Wn = more ? (which ? p.wupa_t() : p.wupb_t()) + ((long)nt2 * 256) * 512 : Wg;
;       const bf16_t* Yn = more ? (which ? p.sbz() : p.nz()) + (long)mt2 * 256 * 512 : Yg;
;       f32x4 acc[8][4]; zero_acc(acc);
;       gemm_core(Wg, 512, Yg, 512, 512, gl, acc, 64, it > 0 || which, Wn, Yn);
.Lmy_D_cont:
	s_mov_b32 s1, 1
	s_mov_b64 s[16:17], 0
	s_and_b64 vcc, exec, s[14:15]
	s_cbranch_vccnz .LBB0_831

; DI int my_tid() { int t = threadIdx.x; asm volatile("" : "+v"(t)); return t; }
; #define G_LDA(dst, ih, ks) _Pragma("unroll") for (int i = 0; i < 4; ++i) dst[i] = mk8(*(const u32x4*)(stage + ra + (((ih) * 4 + i) * 2 + (ks)) * 1024))
; #define G_LDB(dst, ks) _Pragma("unroll") for (int j = 0; j < 4; ++j) dst[j] = mk8(*(const u32x4*)(stage + TILE_B + rb + (j * 2 + (ks)) * 1024))
; DI void g_compute(const unsigned char* stage, int ra, int rb, f32x4 (&acc)[8][4]) {
;   bf16x8 b0[4], b1[4], a0[4], a1[4];
;   G_LDB(b0, 0); G_LDA(a0, 0, 0);
;   __builtin_amdgcn_sched_barrier(0);
;   G_LDA(a1, 1, 0);
;   G_MMA(0, a0, b0);
;   __builtin_amdgcn_sched_barrier(0);
;   G_LDB(b1, 1); G_LDA(a0, 0, 1);
;   G_MMA(1, a1, b0);
;   __builtin_amdgcn_sched_barrier(0);
;   G_LDA(a1, 1, 1);
;   G_MMA(0, a0, b1);
;   __builtin_amdgcn_sched_barrier(0);
;   G_MMA(1, a1, b1);
;   __builtin_amdgcn_sched_barrier(0);
; }
;   unsigned char* lds = (unsigned char*)ldsb;
;   const int tid = my_tid(), lane = tid & 63, w = __builtin_amdgcn_readfirstlane(tid >> 6), wa = w >> 2, wb = w & 3, qi = lane & 15, quad = lane >> 4;
;   const bf16_t* base = w >= 4 ? Bg : Ag; const int ld = (int)(w >= 4 ? ldb : lda);
;   const bf16_t* nbase = nAg ? (w >= 4 ? nBg : nAg) : base;
;   unsigned off[8];
; #pragma unroll
;   for (int u = 0; u < 8; ++u) {
;     const int blk = (w & 3) * 8 + u, rg = blk >> 1, kh = blk & 1;
;     int R = rg * 16 + (lane >> 2);
;     if (perm) { const int rho = R & 31; R = (R & ~31) + ((rho >> 2) & 3) * 8 + (rho >> 4) * 4 + (rho & 3); }
;     off[u] = (unsigned)(R * ld + kh * 32 + (lane & 3) * 8);
;   }
;   const int ra = (wa * 8) * 2 * 1024 + (qi * 4 + quad) * 16, rb = (wb * 4) * 2 * 1024 + (qi * 4 + quad) * 16;
;   unsigned char* buf0 = lds; unsigned char* buf1 = lds + STAGE_B;
;   const int KT = K >> 6;
;   if (!pre) {
;     g_dma(base, off, 0, buf0, w);
;     asm volatile("s_waitcnt vmcnt(0)" ::: "memory");
;     __syncthreads();
;   }
;   for (int kt = 0; kt < KT; kt += 2) {
;     g_dma(base, off, (kt + 1) * kstep, buf1, w);
;     g_compute(buf0, ra, rb, acc);
;     asm volatile("s_waitcnt vmcnt(0)" ::: "memory");
;     __syncthreads();
;     const bool last = kt + 2 >= KT;
;     g_dma(last ? nbase : base, off, last ? 0 : (kt + 2) * kstep, buf0, w);
;     g_compute(buf1, ra, rb, acc);
;     asm volatile("s_waitcnt vmcnt(0)" ::: "memory");
;     __syncthreads();
;   }
.LgD_loop:
	s_waitcnt lgkmcnt(0)
	v_mfma_f32_16x16x32_bf16 v[126:129], v[190:193], v[174:177], v[126:129]
	v_mfma_f32_16x16x32_bf16 v[94:97], v[190:193], v[178:181], v[94:97]
	ds_read_b128 v[206:209], v160 offset:8192
	v_mfma_f32_16x16x32_bf16 v[66:69], v[190:193], v[182:185], v[66:69]
	v_mfma_f32_16x16x32_bf16 v[30:33], v[190:193], v[186:189], v[30:33]
	v_mfma_f32_16x16x32_bf16 v[122:125], v[194:197], v[174:177], v[122:125]
	ds_read_b128 v[216:219], v160 offset:10240
	v_mfma_f32_16x16x32_bf16 v[90:93], v[194:197], v[178:181], v[90:93]
	v_mfma_f32_16x16x32_bf16 v[58:61], v[194:197], v[182:185], v[58:61]
	v_mfma_f32_16x16x32_bf16 v[26:29], v[194:197], v[186:189], v[26:29]
	ds_read_b128 v[220:223], v160 offset:12288
	v_mfma_f32_16x16x32_bf16 v[118:121], v[198:201], v[174:177], v[118:121]
	v_mfma_f32_16x16x32_bf16 v[86:89], v[198:201], v[178:181], v[86:89]
	v_mfma_f32_16x16x32_bf16 v[54:57], v[198:201], v[182:185], v[54:57]
	ds_read_b128 v[224:227], v160 offset:14336
	v_mfma_f32_16x16x32_bf16 v[22:25], v[198:201], v[186:189], v[22:25]
	v_mfma_f32_16x16x32_bf16 v[114:117], v[202:205], v[174:177], v[114:117]
	v_mfma_f32_16x16x32_bf16 v[82:85], v[202:205], v[178:181], v[82:85]
	v_mfma_f32_16x16x32_bf16 v[50:53], v[202:205], v[182:185], v[50:53]
	v_mfma_f32_16x16x32_bf16 v[18:21], v[202:205], v[186:189], v[18:21]
	s_waitcnt lgkmcnt(0)
	v_mfma_f32_16x16x32_bf16 v[110:113], v[206:209], v[174:177], v[110:113]
	ds_read_b128 v[240:243], v162 offset:1024
	v_mfma_f32_16x16x32_bf16 v[78:81], v[206:209], v[178:181], v[78:81]
	v_mfma_f32_16x16x32_bf16 v[46:49], v[206:209], v[182:185], v[46:49]
	ds_read_b128 v[244:247], v162 offset:3072
	v_mfma_f32_16x16x32_bf16 v[14:17], v[206:209], v[186:189], v[14:17]
	v_mfma_f32_16x16x32_bf16 v[106:109], v[216:219], v[174:177], v[106:109]
	ds_read_b128 v[248:251], v162 offset:5120
	v_mfma_f32_16x16x32_bf16 v[74:77], v[216:219], v[178:181], v[74:77]
	v_mfma_f32_16x16x32_bf16 v[42:45], v[216:219], v[182:185], v[42:45]
	ds_read_b128 v[148:151], v162 offset:7168
	v_mfma_f32_16x16x32_bf16 v[10:13], v[216:219], v[186:189], v[10:13]
	v_mfma_f32_16x16x32_bf16 v[102:105], v[220:223], v[174:177], v[102:105]
	ds_read_b128 v[190:193], v160 offset:1024
	v_mfma_f32_16x16x32_bf16 v[70:73], v[220:223], v[178:181], v[70:73]
	ds_read_b128 v[194:197], v160 offset:3072
	v_mfma_f32_16x16x32_bf16 v[38:41], v[220:223], v[182:185], v[38:41]
	ds_read_b128 v[198:201], v160 offset:5120
	v_mfma_f32_16x16x32_bf16 v[6:9], v[220:223], v[186:189], v[6:9]
	ds_read_b128 v[202:205], v160 offset:7168
	v_mfma_f32_16x16x32_bf16 v[98:101], v[224:227], v[174:177], v[98:101]
	v_mfma_f32_16x16x32_bf16 v[62:65], v[224:227], v[178:181], v[62:65]
	v_mfma_f32_16x16x32_bf16 v[34:37], v[224:227], v[182:185], v[34:37]
	v_mfma_f32_16x16x32_bf16 v[2:5], v[224:227], v[186:189], v[2:5]
	s_waitcnt lgkmcnt(0)
	v_mfma_f32_16x16x32_bf16 v[126:129], v[190:193], v[240:243], v[126:129]
	v_mfma_f32_16x16x32_bf16 v[94:97], v[190:193], v[244:247], v[94:97]
	ds_read_b128 v[206:209], v160 offset:9216
	v_mfma_f32_16x16x32_bf16 v[66:69], v[190:193], v[248:251], v[66:69]
	v_mfma_f32_16x16x32_bf16 v[30:33], v[190:193], v[148:151], v[30:33]
	v_mfma_f32_16x16x32_bf16 v[122:125], v[194:197], v[240:243], v[122:125]
	ds_read_b128 v[216:219], v160 offset:11264
	v_mfma_f32_16x16x32_bf16 v[90:93], v[194:197], v[244:247], v[90:93]
	v_mfma_f32_16x16x32_bf16 v[58:61], v[194:197], v[248:251], v[58:61]
	v_mfma_f32_16x16x32_bf16 v[26:29], v[194:197], v[148:151], v[26:29]
	ds_read_b128 v[220:223], v160 offset:13312
	v_mfma_f32_16x16x32_bf16 v[118:121], v[198:201], v[240:243], v[118:121]
	v_mfma_f32_16x16x32_bf16 v[86:89], v[198:201], v[244:247], v[86:89]
	v_mfma_f32_16x16x32_bf16 v[54:57], v[198:201], v[248:251], v[54:57]
	ds_read_b128 v[224:227], v160 offset:15360
	v_mfma_f32_16x16x32_bf16 v[22:25], v[198:201], v[148:151], v[22:25]
	v_mfma_f32_16x16x32_bf16 v[114:117], v[202:205], v[240:243], v[114:117]
	v_mfma_f32_16x16x32_bf16 v[82:85], v[202:205], v[244:247], v[82:85]
	v_mfma_f32_16x16x32_bf16 v[50:53], v[202:205], v[248:251], v[50:53]
	v_mfma_f32_16x16x32_bf16 v[18:21], v[202:205], v[148:151], v[18:21]
	s_waitcnt lgkmcnt(0)
	s_waitcnt vmcnt(0)
	s_barrier
	s_add_i32 m0, s42, 0x0
	v_mfma_f32_16x16x32_bf16 v[110:113], v[206:209], v[240:243], v[110:113]
	global_load_lds_dwordx4 v152, s[38:39]
	ds_read_b128 v[174:177], v163
	v_mfma_f32_16x16x32_bf16 v[78:81], v[206:209], v[244:247], v[78:81]
	ds_read_b128 v[178:181], v163 offset:2048
	s_add_i32 m0, s42, 0x400
	v_mfma_f32_16x16x32_bf16 v[46:49], v[206:209], v[248:251], v[46:49]
	global_load_lds_dwordx4 v153, s[38:39]
	ds_read_b128 v[182:185], v163 offset:4096
	v_mfma_f32_16x16x32_bf16 v[14:17], v[206:209], v[148:151], v[14:17]
	ds_read_b128 v[186:189], v163 offset:6144
	s_add_i32 m0, s42, 0x800
	v_mfma_f32_16x16x32_bf16 v[106:109], v[216:219], v[240:243], v[106:109]
	global_load_lds_dwordx4 v154, s[38:39]
	ds_read_b128 v[190:193], v161
	v_mfma_f32_16x16x32_bf16 v[74:77], v[216:219], v[244:247], v[74:77]
	ds_read_b128 v[194:197], v161 offset:2048
	s_add_i32 m0, s42, 0xc00
	v_mfma_f32_16x16x32_bf16 v[42:45], v[216:219], v[248:251], v[42:45]
	global_load_lds_dwordx4 v155, s[38:39]
	ds_read_b128 v[198:201], v161 offset:4096
	v_mfma_f32_16x16x32_bf16 v[10:13], v[216:219], v[148:151], v[10:13]
	ds_read_b128 v[202:205], v161 offset:6144
	s_add_i32 m0, s42, 0x1000
	v_mfma_f32_16x16x32_bf16 v[102:105], v[220:223], v[240:243], v[102:105]
	global_load_lds_dwordx4 v156, s[38:39]
	v_mfma_f32_16x16x32_bf16 v[70:73], v[220:223], v[244:247], v[70:73]
	s_add_i32 m0, s42, 0x1400
	v_mfma_f32_16x16x32_bf16 v[38:41], v[220:223], v[248:251], v[38:41]
	global_load_lds_dwordx4 v157, s[38:39]
	v_mfma_f32_16x16x32_bf16 v[6:9], v[220:223], v[148:151], v[6:9]
	s_add_i32 m0, s42, 0x1800
	v_mfma_f32_16x16x32_bf16 v[98:101], v[224:227], v[240:243], v[98:101]
	global_load_lds_dwordx4 v158, s[38:39]
	v_mfma_f32_16x16x32_bf16 v[62:65], v[224:227], v[244:247], v[62:65]
	s_add_i32 m0, s42, 0x1c00
	v_mfma_f32_16x16x32_bf16 v[34:37], v[224:227], v[248:251], v[34:37]
	global_load_lds_dwordx4 v159, s[38:39]
	v_mfma_f32_16x16x32_bf16 v[2:5], v[224:227], v[148:151], v[2:5]
	s_add_u32 s38, s38, 0x80
	s_addc_u32 s39, s39, 0
	s_waitcnt lgkmcnt(0)
; DI int my_tid() { int t = threadIdx.x; asm volatile("" : "+v"(t)); return t; }
; #define G_LDA(dst, ih, ks) _Pragma("unroll") for (int i = 0; i < 4; ++i) dst[i] = mk8(*(const u32x4*)(stage + ra + (((ih) * 4 + i) * 2 + (ks)) * 1024))
; #define G_LDB(dst, ks) _Pragma("unroll") for (int j = 0; j < 4; ++j) dst[j] = mk8(*(const u32x4*)(stage + TILE_B + rb + (j * 2 + (ks)) * 1024))
; DI void g_compute(const unsigned char* stage, int ra, int rb, f32x4 (&acc)[8][4]) {
;   bf16x8 b0[4], b1[4], a0[4], a1[4];
;   G_LDB(b0, 0); G_LDA(a0, 0, 0);
;   __builtin_amdgcn_sched_barrier(0);
;   G_LDA(a1, 1, 0);
;   G_MMA(0, a0, b0);
;   __builtin_amdgcn_sched_barrier(0);
;   G_LDB(b1, 1); G_LDA(a0, 0, 1);
;   G_MMA(1, a1, b0);
;   __builtin_amdgcn_sched_barrier(0);
;   G_LDA(a1, 1, 1);
;   G_MMA(0, a0, b1);
;   __builtin_amdgcn_sched_barrier(0);
;   G_MMA(1, a1, b1);
;   __builtin_amdgcn_sched_barrier(0);
; }
;   unsigned char* lds = (unsigned char*)ldsb;
;   const int tid = my_tid(), lane = tid & 63, w = __builtin_amdgcn_readfirstlane(tid >> 6), wa = w >> 2, wb = w & 3, qi = lane & 15, quad = lane >> 4;
;   const bf16_t* base = w >= 4 ? Bg : Ag; const int ld = (int)(w >= 4 ? ldb : lda);
;   const bf16_t* nbase = nAg ? (w >= 4 ? nBg : nAg) : base;
;   unsigned off[8];
; #pragma unroll
;   for (int u = 0; u < 8; ++u) {
;     const int blk = (w & 3) * 8 + u, rg = blk >> 1, kh = blk & 1;
;     int R = rg * 16 + (lane >> 2);
;     if (perm) { const int rho = R & 31; R = (R & ~31) + ((rho >> 2) & 3) * 8 + (rho >> 4) * 4 + (rho & 3); }
;     off[u] = (unsigned)(R * ld + kh * 32 + (lane & 3) * 8);
;   }
;   const int ra = (wa * 8) * 2 * 1024 + (qi * 4 + quad) * 16, rb = (wb * 4) * 2 * 1024 + (qi * 4 + quad) * 16;
;   unsigned char* buf0 = lds; unsigned char* buf1 = lds + STAGE_B;
;   const int KT = K >> 6;
;   if (!pre) {
;     g_dma(base, off, 0, buf0, w);
;     asm volatile("s_waitcnt vmcnt(0)" ::: "memory");
;     __syncthreads();
;   }
;   for (int kt = 0; kt < KT; kt += 2) {
;     g_dma(base, off, (kt + 1) * kstep, buf1, w);
;     g_compute(buf0, ra, rb, acc);
;     asm volatile("s_waitcnt vmcnt(0)" ::: "memory");
;     __syncthreads();
;     const bool last = kt + 2 >= KT;
;     g_dma(last ? nbase : base, off, last ? 0 : (kt + 2) * kstep, buf0, w);
;     g_compute(buf1, ra, rb, acc);
;     asm volatile("s_waitcnt vmcnt(0)" ::: "memory");
;     __syncthreads();
;   }
	v_mfma_f32_16x16x32_bf16 v[126:129], v[190:193], v[174:177], v[126:129]
	v_mfma_f32_16x16x32_bf16 v[94:97], v[190:193], v[178:181], v[94:97]
	ds_read_b128 v[206:209], v161 offset:8192
	v_mfma_f32_16x16x32_bf16 v[66:69], v[190:193], v[182:185], v[66:69]
	v_mfma_f32_16x16x32_bf16 v[30:33], v[190:193], v[186:189], v[30:33]
	v_mfma_f32_16x16x32_bf16 v[122:125], v[194:197], v[174:177], v[122:125]
	ds_read_b128 v[216:219], v161 offset:10240
	v_mfma_f32_16x16x32_bf16 v[90:93], v[194:197], v[178:181], v[90:93]
	v_mfma_f32_16x16x32_bf16 v[58:61], v[194:197], v[182:185], v[58:61]
	v_mfma_f32_16x16x32_bf16 v[26:29], v[194:197], v[186:189], v[26:29]
	ds_read_b128 v[220:223], v161 offset:12288
	v_mfma_f32_16x16x32_bf16 v[118:121], v[198:201], v[174:177], v[118:121]
	v_mfma_f32_16x16x32_bf16 v[86:89], v[198:201], v[178:181], v[86:89]
	v_mfma_f32_16x16x32_bf16 v[54:57], v[198:201], v[182:185], v[54:57]
	ds_read_b128 v[224:227], v161 offset:14336
	v_mfma_f32_16x16x32_bf16 v[22:25], v[198:201], v[186:189], v[22:25]
	v_mfma_f32_16x16x32_bf16 v[114:117], v[202:205], v[174:177], v[114:117]
	v_mfma_f32_16x16x32_bf16 v[82:85], v[202:205], v[178:181], v[82:85]
	v_mfma_f32_16x16x32_bf16 v[50:53], v[202:205], v[182:185], v[50:53]
	v_mfma_f32_16x16x32_bf16 v[18:21], v[202:205], v[186:189], v[18:21]
	s_waitcnt lgkmcnt(0)
	v_mfma_f32_16x16x32_bf16 v[110:113], v[206:209], v[174:177], v[110:113]
	ds_read_b128 v[240:243], v163 offset:1024
	v_mfma_f32_16x16x32_bf16 v[78:81], v[206:209], v[178:181], v[78:81]
	v_mfma_f32_16x16x32_bf16 v[46:49], v[206:209], v[182:185], v[46:49]
	ds_read_b128 v[244:247], v163 offset:3072
	v_mfma_f32_16x16x32_bf16 v[14:17], v[206:209], v[186:189], v[14:17]
	v_mfma_f32_16x16x32_bf16 v[106:109], v[216:219], v[174:177], v[106:109]
	ds_read_b128 v[248:251], v163 offset:5120
	v_mfma_f32_16x16x32_bf16 v[74:77], v[216:219], v[178:181], v[74:77]
	v_mfma_f32_16x16x32_bf16 v[42:45], v[216:219], v[182:185], v[42:45]
	ds_read_b128 v[148:151], v163 offset:7168
	v_mfma_f32_16x16x32_bf16 v[10:13], v[216:219], v[186:189], v[10:13]
	v_mfma_f32_16x16x32_bf16 v[102:105], v[220:223], v[174:177], v[102:105]
	ds_read_b128 v[190:193], v161 offset:1024
	v_mfma_f32_16x16x32_bf16 v[70:73], v[220:223], v[178:181], v[70:73]
	ds_read_b128 v[194:197], v161 offset:3072
	v_mfma_f32_16x16x32_bf16 v[38:41], v[220:223], v[182:185], v[38:41]
	ds_read_b128 v[198:201], v161 offset:5120
	v_mfma_f32_16x16x32_bf16 v[6:9], v[220:223], v[186:189], v[6:9]
	ds_read_b128 v[202:205], v161 offset:7168
	v_mfma_f32_16x16x32_bf16 v[98:101], v[224:227], v[174:177], v[98:101]
	v_mfma_f32_16x16x32_bf16 v[62:65], v[224:227], v[178:181], v[62:65]
	v_mfma_f32_16x16x32_bf16 v[34:37], v[224:227], v[182:185], v[34:37]
	v_mfma_f32_16x16x32_bf16 v[2:5], v[224:227], v[186:189], v[2:5]
	s_waitcnt lgkmcnt(0)
	v_mfma_f32_16x16x32_bf16 v[126:129], v[190:193], v[240:243], v[126:129]
	v_mfma_f32_16x16x32_bf16 v[94:97], v[190:193], v[244:247], v[94:97]
	ds_read_b128 v[206:209], v161 offset:9216
	v_mfma_f32_16x16x32_bf16 v[66:69], v[190:193], v[248:251], v[66:69]
	v_mfma_f32_16x16x32_bf16 v[30:33], v[190:193], v[148:151], v[30:33]
	v_mfma_f32_16x16x32_bf16 v[122:125], v[194:197], v[240:243], v[122:125]
	ds_read_b128 v[216:219], v161 offset:11264
	v_mfma_f32_16x16x32_bf16 v[90:93], v[194:197], v[244:247], v[90:93]
	v_mfma_f32_16x16x32_bf16 v[58:61], v[194:197], v[248:251], v[58:61]
	v_mfma_f32_16x16x32_bf16 v[26:29], v[194:197], v[148:151], v[26:29]
	ds_read_b128 v[220:223], v161 offset:13312
	v_mfma_f32_16x16x32_bf16 v[118:121], v[198:201], v[240:243], v[118:121]
	v_mfma_f32_16x16x32_bf16 v[86:89], v[198:201], v[244:247], v[86:89]
	v_mfma_f32_16x16x32_bf16 v[54:57], v[198:201], v[248:251], v[54:57]
	ds_read_b128 v[224:227], v161 offset:15360
	v_mfma_f32_16x16x32_bf16 v[22:25], v[198:201], v[148:151], v[22:25]
	v_mfma_f32_16x16x32_bf16 v[114:117], v[202:205], v[240:243], v[114:117]
	v_mfma_f32_16x16x32_bf16 v[82:85], v[202:205], v[244:247], v[82:85]
	v_mfma_f32_16x16x32_bf16 v[50:53], v[202:205], v[248:251], v[50:53]
	v_mfma_f32_16x16x32_bf16 v[18:21], v[202:205], v[148:151], v[18:21]
	s_waitcnt lgkmcnt(0)
	s_waitcnt vmcnt(0)
	s_barrier
	s_add_i32 m0, s43, 0x0
	v_mfma_f32_16x16x32_bf16 v[110:113], v[206:209], v[240:243], v[110:113]
	global_load_lds_dwordx4 v152, s[38:39]
	ds_read_b128 v[174:177], v162
	v_mfma_f32_16x16x32_bf16 v[78:81], v[206:209], v[244:247], v[78:81]
	ds_read_b128 v[178:181], v162 offset:2048
	s_add_i32 m0, s43, 0x400
	v_mfma_f32_16x16x32_bf16 v[46:49], v[206:209], v[248:251], v[46:49]
	global_load_lds_dwordx4 v153, s[38:39]
	ds_read_b128 v[182:185], v162 offset:4096
	v_mfma_f32_16x16x32_bf16 v[14:17], v[206:209], v[148:151], v[14:17]
	ds_read_b128 v[186:189], v162 offset:6144
	s_add_i32 m0, s43, 0x800
	v_mfma_f32_16x16x32_bf16 v[106:109], v[216:219], v[240:243], v[106:109]
	global_load_lds_dwordx4 v154, s[38:39]
	ds_read_b128 v[190:193], v160
	v_mfma_f32_16x16x32_bf16 v[74:77], v[216:219], v[244:247], v[74:77]
	ds_read_b128 v[194:197], v160 offset:2048
	s_add_i32 m0, s43, 0xc00
	v_mfma_f32_16x16x32_bf16 v[42:45], v[216:219], v[248:251], v[42:45]
	global_load_lds_dwordx4 v155, s[38:39]
	ds_read_b128 v[198:201], v160 offset:4096
	v_mfma_f32_16x16x32_bf16 v[10:13], v[216:219], v[148:151], v[10:13]
	ds_read_b128 v[202:205], v160 offset:6144
	s_add_i32 m0, s43, 0x1000
	v_mfma_f32_16x16x32_bf16 v[102:105], v[220:223], v[240:243], v[102:105]
	global_load_lds_dwordx4 v156, s[38:39]
	v_mfma_f32_16x16x32_bf16 v[70:73], v[220:223], v[244:247], v[70:73]
	s_add_i32 m0, s43, 0x1400
	v_mfma_f32_16x16x32_bf16 v[38:41], v[220:223], v[248:251], v[38:41]
	global_load_lds_dwordx4 v157, s[38:39]
	v_mfma_f32_16x16x32_bf16 v[6:9], v[220:223], v[148:151], v[6:9]
	s_add_i32 m0, s43, 0x1800
	v_mfma_f32_16x16x32_bf16 v[98:101], v[224:227], v[240:243], v[98:101]
	global_load_lds_dwordx4 v158, s[38:39]
	v_mfma_f32_16x16x32_bf16 v[62:65], v[224:227], v[244:247], v[62:65]
	s_add_i32 m0, s43, 0x1c00
	v_mfma_f32_16x16x32_bf16 v[34:37], v[224:227], v[248:251], v[34:37]
	global_load_lds_dwordx4 v159, s[38:39]
	v_mfma_f32_16x16x32_bf16 v[2:5], v[224:227], v[148:151], v[2:5]
	s_add_u32 s38, s38, 0x80
	s_addc_u32 s39, s39, 0
	s_add_i32 s48, s48, 1
	s_cmp_lt_u32 s48, 3
	s_cbranch_scc1 .LgD_loop
; DI int my_tid() { int t = threadIdx.x; asm volatile("" : "+v"(t)); return t; }
; #define G_LDA(dst, ih, ks) _Pragma("unroll") for (int i = 0; i < 4; ++i) dst[i] = mk8(*(const u32x4*)(stage + ra + (((ih) * 4 + i) * 2 + (ks)) * 1024))
; #define G_LDB(dst, ks) _Pragma("unroll") for (int j = 0; j < 4; ++j) dst[j] = mk8(*(const u32x4*)(stage + TILE_B + rb + (j * 2 + (ks)) * 1024))
; DI void g_compute(const unsigned char* stage, int ra, int rb, f32x4 (&acc)[8][4]) {
;   bf16x8 b0[4], b1[4], a0[4], a1[4];
;   G_LDB(b0, 0); G_LDA(a0, 0, 0);
;   __builtin_amdgcn_sched_barrier(0);
;   G_LDA(a1, 1, 0);
;   G_MMA(0, a0, b0);
;   __builtin_amdgcn_sched_barrier(0);
;   G_LDB(b1, 1); G_LDA(a0, 0, 1);
;   G_MMA(1, a1, b0);
;   __builtin_amdgcn_sched_barrier(0);
;   G_LDA(a1, 1, 1);
;   G_MMA(0, a0, b1);
;   __builtin_amdgcn_sched_barrier(0);
;   G_MMA(1, a1, b1);
;   __builtin_amdgcn_sched_barrier(0);
; }
;   unsigned char* lds = (unsigned char*)ldsb;
;   const int tid = my_tid(), lane = tid & 63, w = __builtin_amdgcn_readfirstlane(tid >> 6), wa = w >> 2, wb = w & 3, qi = lane & 15, quad = lane >> 4;
;   const bf16_t* base = w >= 4 ? Bg : Ag; const int ld = (int)(w >= 4 ? ldb : lda);
;   const bf16_t* nbase = nAg ? (w >= 4 ? nBg : nAg) : base;
;   unsigned off[8];
; #pragma unroll
;   for (int u = 0; u < 8; ++u) {
;     const int blk = (w & 3) * 8 + u, rg = blk >> 1, kh = blk & 1;
;     int R = rg * 16 + (lane >> 2);
;     if (perm) { const int rho = R & 31; R = (R & ~31) + ((rho >> 2) & 3) * 8 + (rho >> 4) * 4 + (rho & 3); }
;     off[u] = (unsigned)(R * ld + kh * 32 + (lane & 3) * 8);
;   }
;   const int ra = (wa * 8) * 2 * 1024 + (qi * 4 + quad) * 16, rb = (wb * 4) * 2 * 1024 + (qi * 4 + quad) * 16;
;   unsigned char* buf0 = lds; unsigned char* buf1 = lds + STAGE_B;
;   const int KT = K >> 6;
;   if (!pre) {
;     g_dma(base, off, 0, buf0, w);
;     asm volatile("s_waitcnt vmcnt(0)" ::: "memory");
;     __syncthreads();
;   }
;   for (int kt = 0; kt < KT; kt += 2) {
;     g_dma(base, off, (kt + 1) * kstep, buf1, w);
;     g_compute(buf0, ra, rb, acc);
;     asm volatile("s_waitcnt vmcnt(0)" ::: "memory");
;     __syncthreads();
;     const bool last = kt + 2 >= KT;
;     g_dma(last ? nbase : base, off, last ? 0 : (kt + 2) * kstep, buf0, w);
;     g_compute(buf1, ra, rb, acc);
;     asm volatile("s_waitcnt vmcnt(0)" ::: "memory");
;     __syncthreads();
;   }
	s_waitcnt lgkmcnt(0)
	v_mfma_f32_16x16x32_bf16 v[126:129], v[190:193], v[174:177], v[126:129]
	v_mfma_f32_16x16x32_bf16 v[94:97], v[190:193], v[178:181], v[94:97]
	ds_read_b128 v[206:209], v160 offset:8192
	v_mfma_f32_16x16x32_bf16 v[66:69], v[190:193], v[182:185], v[66:69]
	v_mfma_f32_16x16x32_bf16 v[30:33], v[190:193], v[186:189], v[30:33]
	v_mfma_f32_16x16x32_bf16 v[122:125], v[194:197], v[174:177], v[122:125]
	ds_read_b128 v[216:219], v160 offset:10240
	v_mfma_f32_16x16x32_bf16 v[90:93], v[194:197], v[178:181], v[90:93]
	v_mfma_f32_16x16x32_bf16 v[58:61], v[194:197], v[182:185], v[58:61]
	v_mfma_f32_16x16x32_bf16 v[26:29], v[194:197], v[186:189], v[26:29]
	ds_read_b128 v[220:223], v160 offset:12288
	v_mfma_f32_16x16x32_bf16 v[118:121], v[198:201], v[174:177], v[118:121]
	v_mfma_f32_16x16x32_bf16 v[86:89], v[198:201], v[178:181], v[86:89]
	v_mfma_f32_16x16x32_bf16 v[54:57], v[198:201], v[182:185], v[54:57]
	ds_read_b128 v[224:227], v160 offset:14336
	v_mfma_f32_16x16x32_bf16 v[22:25], v[198:201], v[186:189], v[22:25]
	v_mfma_f32_16x16x32_bf16 v[114:117], v[202:205], v[174:177], v[114:117]
	v_mfma_f32_16x16x32_bf16 v[82:85], v[202:205], v[178:181], v[82:85]
	v_mfma_f32_16x16x32_bf16 v[50:53], v[202:205], v[182:185], v[50:53]
	v_mfma_f32_16x16x32_bf16 v[18:21], v[202:205], v[186:189], v[18:21]
	s_waitcnt lgkmcnt(0)
	v_mfma_f32_16x16x32_bf16 v[110:113], v[206:209], v[174:177], v[110:113]
	ds_read_b128 v[240:243], v162 offset:1024
	v_mfma_f32_16x16x32_bf16 v[78:81], v[206:209], v[178:181], v[78:81]
	v_mfma_f32_16x16x32_bf16 v[46:49], v[206:209], v[182:185], v[46:49]
	ds_read_b128 v[244:247], v162 offset:3072
	v_mfma_f32_16x16x32_bf16 v[14:17], v[206:209], v[186:189], v[14:17]
	v_mfma_f32_16x16x32_bf16 v[106:109], v[216:219], v[174:177], v[106:109]
	ds_read_b128 v[248:251], v162 offset:5120
	v_mfma_f32_16x16x32_bf16 v[74:77], v[216:219], v[178:181], v[74:77]
	v_mfma_f32_16x16x32_bf16 v[42:45], v[216:219], v[182:185], v[42:45]
	ds_read_b128 v[148:151], v162 offset:7168
	v_mfma_f32_16x16x32_bf16 v[10:13], v[216:219], v[186:189], v[10:13]
	v_mfma_f32_16x16x32_bf16 v[102:105], v[220:223], v[174:177], v[102:105]
	ds_read_b128 v[190:193], v160 offset:1024
	v_mfma_f32_16x16x32_bf16 v[70:73], v[220:223], v[178:181], v[70:73]
	ds_read_b128 v[194:197], v160 offset:3072
	v_mfma_f32_16x16x32_bf16 v[38:41], v[220:223], v[182:185], v[38:41]
	ds_read_b128 v[198:201], v160 offset:5120
	v_mfma_f32_16x16x32_bf16 v[6:9], v[220:223], v[186:189], v[6:9]
	ds_read_b128 v[202:205], v160 offset:7168
	v_mfma_f32_16x16x32_bf16 v[98:101], v[224:227], v[174:177], v[98:101]
	v_mfma_f32_16x16x32_bf16 v[62:65], v[224:227], v[178:181], v[62:65]
	v_mfma_f32_16x16x32_bf16 v[34:37], v[224:227], v[182:185], v[34:37]
	v_mfma_f32_16x16x32_bf16 v[2:5], v[224:227], v[186:189], v[2:5]
	s_waitcnt lgkmcnt(0)
	v_mfma_f32_16x16x32_bf16 v[126:129], v[190:193], v[240:243], v[126:129]
	v_mfma_f32_16x16x32_bf16 v[94:97], v[190:193], v[244:247], v[94:97]
	ds_read_b128 v[206:209], v160 offset:9216
	v_mfma_f32_16x16x32_bf16 v[66:69], v[190:193], v[248:251], v[66:69]
	v_mfma_f32_16x16x32_bf16 v[30:33], v[190:193], v[148:151], v[30:33]
	v_mfma_f32_16x16x32_bf16 v[122:125], v[194:197], v[240:243], v[122:125]
	ds_read_b128 v[216:219], v160 offset:11264
	v_mfma_f32_16x16x32_bf16 v[90:93], v[194:197], v[244:247], v[90:93]
	v_mfma_f32_16x16x32_bf16 v[58:61], v[194:197], v[248:251], v[58:61]
	v_mfma_f32_16x16x32_bf16 v[26:29], v[194:197], v[148:151], v[26:29]
	ds_read_b128 v[220:223], v160 offset:13312
	v_mfma_f32_16x16x32_bf16 v[118:121], v[198:201], v[240:243], v[118:121]
	v_mfma_f32_16x16x32_bf16 v[86:89], v[198:201], v[244:247], v[86:89]
	v_mfma_f32_16x16x32_bf16 v[54:57], v[198:201], v[248:251], v[54:57]
	ds_read_b128 v[224:227], v160 offset:15360
	v_mfma_f32_16x16x32_bf16 v[22:25], v[198:201], v[148:151], v[22:25]
	v_mfma_f32_16x16x32_bf16 v[114:117], v[202:205], v[240:243], v[114:117]
	v_mfma_f32_16x16x32_bf16 v[82:85], v[202:205], v[244:247], v[82:85]
	v_mfma_f32_16x16x32_bf16 v[50:53], v[202:205], v[248:251], v[50:53]
	v_mfma_f32_16x16x32_bf16 v[18:21], v[202:205], v[148:151], v[18:21]
	s_waitcnt lgkmcnt(0)
	s_waitcnt vmcnt(0)
	s_barrier
	s_add_i32 m0, s42, 0x0
	v_mfma_f32_16x16x32_bf16 v[110:113], v[206:209], v[240:243], v[110:113]
	global_load_lds_dwordx4 v152, s[40:41]
	ds_read_b128 v[174:177], v163
	v_mfma_f32_16x16x32_bf16 v[78:81], v[206:209], v[244:247], v[78:81]
	ds_read_b128 v[178:181], v163 offset:2048
	s_add_i32 m0, s42, 0x400
	v_mfma_f32_16x16x32_bf16 v[46:49], v[206:209], v[248:251], v[46:49]
	global_load_lds_dwordx4 v153, s[40:41]
	ds_read_b128 v[182:185], v163 offset:4096
	v_mfma_f32_16x16x32_bf16 v[14:17], v[206:209], v[148:151], v[14:17]
	ds_read_b128 v[186:189], v163 offset:6144
	s_add_i32 m0, s42, 0x800
	v_mfma_f32_16x16x32_bf16 v[106:109], v[216:219], v[240:243], v[106:109]
	global_load_lds_dwordx4 v154, s[40:41]
	ds_read_b128 v[190:193], v161
	v_mfma_f32_16x16x32_bf16 v[74:77], v[216:219], v[244:247], v[74:77]
	ds_read_b128 v[194:197], v161 offset:2048
	s_add_i32 m0, s42, 0xc00
	v_mfma_f32_16x16x32_bf16 v[42:45], v[216:219], v[248:251], v[42:45]
	global_load_lds_dwordx4 v155, s[40:41]
	ds_read_b128 v[198:201], v161 offset:4096
	v_mfma_f32_16x16x32_bf16 v[10:13], v[216:219], v[148:151], v[10:13]
	ds_read_b128 v[202:205], v161 offset:6144
	s_add_i32 m0, s42, 0x1000
	v_mfma_f32_16x16x32_bf16 v[102:105], v[220:223], v[240:243], v[102:105]
	global_load_lds_dwordx4 v156, s[40:41]
	v_mfma_f32_16x16x32_bf16 v[70:73], v[220:223], v[244:247], v[70:73]
	s_add_i32 m0, s42, 0x1400
	v_mfma_f32_16x16x32_bf16 v[38:41], v[220:223], v[248:251], v[38:41]
	global_load_lds_dwordx4 v157, s[40:41]
	v_mfma_f32_16x16x32_bf16 v[6:9], v[220:223], v[148:151], v[6:9]
	s_add_i32 m0, s42, 0x1800
	v_mfma_f32_16x16x32_bf16 v[98:101], v[224:227], v[240:243], v[98:101]
	global_load_lds_dwordx4 v158, s[40:41]
	v_mfma_f32_16x16x32_bf16 v[62:65], v[224:227], v[244:247], v[62:65]
	s_add_i32 m0, s42, 0x1c00
	v_mfma_f32_16x16x32_bf16 v[34:37], v[224:227], v[248:251], v[34:37]
	global_load_lds_dwordx4 v159, s[40:41]
	v_mfma_f32_16x16x32_bf16 v[2:5], v[224:227], v[148:151], v[2:5]
	s_add_u32 s40, s40, 0x80
	s_addc_u32 s41, s41, 0
	s_waitcnt lgkmcnt(0)
; DI unsigned pk2(float lo, float hi) { f32x2 v = {lo, hi}; bf16x2_t b = __builtin_convertvector(v, bf16x2_t); return __builtin_bit_cast(unsigned, b); }
; DI float bflo(unsigned u) { return __uint_as_float(u << 16); }
; DI float bfhi(unsigned u) { return __uint_as_float(u & 0xffff0000u); }
; DI int my_tid() { int t = threadIdx.x; asm volatile("" : "+v"(t)); return t; }
; #define G_LDA(dst, ih, ks) _Pragma("unroll") for (int i = 0; i < 4; ++i) dst[i] = mk8(*(const u32x4*)(stage + ra + (((ih) * 4 + i) * 2 + (ks)) * 1024))
; #define G_LDB(dst, ks) _Pragma("unroll") for (int j = 0; j < 4; ++j) dst[j] = mk8(*(const u32x4*)(stage + TILE_B + rb + (j * 2 + (ks)) * 1024))
; #define G_MMA(ih, A, B) do { _Pragma("unroll") for (int i = 0; i < 4; ++i) _Pragma("unroll") for (int j = 0; j < 4; ++j) acc[(ih) * 4 + i][j] = MFMA16(A[i], B[j], acc[(ih) * 4 + i][j]); } while (0)
; DI void g_compute(const unsigned char* stage, int ra, int rb, f32x4 (&acc)[8][4]) {
;   bf16x8 b0[4], b1[4], a0[4], a1[4];
;   G_LDB(b0, 0); G_LDA(a0, 0, 0);
;   __builtin_amdgcn_sched_barrier(0);
;   G_LDA(a1, 1, 0);
;   G_MMA(0, a0, b0);
;   __builtin_amdgcn_sched_barrier(0);
;   G_LDB(b1, 1); G_LDA(a0, 0, 1);
;   G_MMA(1, a1, b0);
;   __builtin_amdgcn_sched_barrier(0);
;   G_LDA(a1, 1, 1);
;   G_MMA(0, a0, b1);
;   __builtin_amdgcn_sched_barrier(0);
;   G_MMA(1, a1, b1);
;   __builtin_amdgcn_sched_barrier(0);
; }
; DI void phaseD(const Params& p0, const Slot sl, int layer, unsigned char* lds) {
;     ...
;       const int tid = my_tid(), lane = tid & 63, w = tid >> 6, wa = w >> 2, wb = w & 3, qi = lane & 15, quad = lane >> 4;
; #pragma unroll
;       for (int j = 0; j < 4; ++j) {
;         const long tok = (long)mt * 256 + wb * 64 + j * 16 + qi;
; #pragma unroll
;         for (int i = 0; i < 8; ++i) {
;           const long off = tok * 1024 + nt * 256 + wa * 128 + i * 16 + quad * 4;
;           const u32x2 xg = *(const u32x2*)(Gg + off);
;           const f32x4 v = acc[i][j];
;           float o0 = bflo(xg[0]) * v[0], o1 = bfhi(xg[0]) * v[1], o2 = bflo(xg[1]) * v[2], o3 = bfhi(xg[1]) * v[3];
;           if (which) { const u32x2 a = *(const u32x2*)(p.merged() + off); o0 += bflo(a[0]); o1 += bfhi(a[0]); o2 += bflo(a[1]); o3 += bfhi(a[1]); }
;           *(u32x2*)(p.merged() + off) = (u32x2){pk2(o0, o1), pk2(o2, o3)};
	v_mfma_f32_16x16x32_bf16 v[126:129], v[190:193], v[174:177], v[126:129]
	v_mfma_f32_16x16x32_bf16 v[94:97], v[190:193], v[178:181], v[94:97]
	ds_read_b128 v[206:209], v161 offset:8192
	v_mfma_f32_16x16x32_bf16 v[66:69], v[190:193], v[182:185], v[66:69]
	v_mfma_f32_16x16x32_bf16 v[30:33], v[190:193], v[186:189], v[30:33]
	v_mfma_f32_16x16x32_bf16 v[122:125], v[194:197], v[174:177], v[122:125]
	ds_read_b128 v[216:219], v161 offset:10240
	v_mfma_f32_16x16x32_bf16 v[90:93], v[194:197], v[178:181], v[90:93]
	v_mfma_f32_16x16x32_bf16 v[58:61], v[194:197], v[182:185], v[58:61]
	v_mfma_f32_16x16x32_bf16 v[26:29], v[194:197], v[186:189], v[26:29]
	ds_read_b128 v[220:223], v161 offset:12288
	v_mfma_f32_16x16x32_bf16 v[118:121], v[198:201], v[174:177], v[118:121]
	v_mfma_f32_16x16x32_bf16 v[86:89], v[198:201], v[178:181], v[86:89]
	v_mfma_f32_16x16x32_bf16 v[54:57], v[198:201], v[182:185], v[54:57]
	ds_read_b128 v[224:227], v161 offset:14336
	v_mfma_f32_16x16x32_bf16 v[22:25], v[198:201], v[186:189], v[22:25]
	v_mfma_f32_16x16x32_bf16 v[114:117], v[202:205], v[174:177], v[114:117]
	v_mfma_f32_16x16x32_bf16 v[82:85], v[202:205], v[178:181], v[82:85]
	v_mfma_f32_16x16x32_bf16 v[50:53], v[202:205], v[182:185], v[50:53]
	v_mfma_f32_16x16x32_bf16 v[18:21], v[202:205], v[186:189], v[18:21]
	s_waitcnt lgkmcnt(0)
	v_mfma_f32_16x16x32_bf16 v[110:113], v[206:209], v[174:177], v[110:113]
	ds_read_b128 v[240:243], v163 offset:1024
	v_mfma_f32_16x16x32_bf16 v[78:81], v[206:209], v[178:181], v[78:81]
	v_mfma_f32_16x16x32_bf16 v[46:49], v[206:209], v[182:185], v[46:49]
	ds_read_b128 v[244:247], v163 offset:3072
	v_mfma_f32_16x16x32_bf16 v[14:17], v[206:209], v[186:189], v[14:17]
	v_mfma_f32_16x16x32_bf16 v[106:109], v[216:219], v[174:177], v[106:109]
	ds_read_b128 v[248:251], v163 offset:5120
	v_mfma_f32_16x16x32_bf16 v[74:77], v[216:219], v[178:181], v[74:77]
	v_mfma_f32_16x16x32_bf16 v[42:45], v[216:219], v[182:185], v[42:45]
	ds_read_b128 v[148:151], v163 offset:7168
	v_mfma_f32_16x16x32_bf16 v[10:13], v[216:219], v[186:189], v[10:13]
	v_mfma_f32_16x16x32_bf16 v[102:105], v[220:223], v[174:177], v[102:105]
	ds_read_b128 v[190:193], v161 offset:1024
	v_mfma_f32_16x16x32_bf16 v[70:73], v[220:223], v[178:181], v[70:73]
	ds_read_b128 v[194:197], v161 offset:3072
	v_mfma_f32_16x16x32_bf16 v[38:41], v[220:223], v[182:185], v[38:41]
	ds_read_b128 v[198:201], v161 offset:5120
	v_mfma_f32_16x16x32_bf16 v[6:9], v[220:223], v[186:189], v[6:9]
	ds_read_b128 v[202:205], v161 offset:7168
	v_mfma_f32_16x16x32_bf16 v[98:101], v[224:227], v[174:177], v[98:101]
	v_mfma_f32_16x16x32_bf16 v[62:65], v[224:227], v[178:181], v[62:65]
	v_mfma_f32_16x16x32_bf16 v[34:37], v[224:227], v[182:185], v[34:37]
	v_mfma_f32_16x16x32_bf16 v[2:5], v[224:227], v[186:189], v[2:5]
	s_waitcnt lgkmcnt(0)
	v_mfma_f32_16x16x32_bf16 v[126:129], v[190:193], v[240:243], v[126:129]
	v_mfma_f32_16x16x32_bf16 v[94:97], v[190:193], v[244:247], v[94:97]
	ds_read_b128 v[206:209], v161 offset:9216
	v_mfma_f32_16x16x32_bf16 v[66:69], v[190:193], v[248:251], v[66:69]
	v_mfma_f32_16x16x32_bf16 v[30:33], v[190:193], v[148:151], v[30:33]
	v_mfma_f32_16x16x32_bf16 v[122:125], v[194:197], v[240:243], v[122:125]
	ds_read_b128 v[216:219], v161 offset:11264
	v_mfma_f32_16x16x32_bf16 v[90:93], v[194:197], v[244:247], v[90:93]
	v_mfma_f32_16x16x32_bf16 v[58:61], v[194:197], v[248:251], v[58:61]
	v_mfma_f32_16x16x32_bf16 v[26:29], v[194:197], v[148:151], v[26:29]
	ds_read_b128 v[220:223], v161 offset:13312
	v_mfma_f32_16x16x32_bf16 v[118:121], v[198:201], v[240:243], v[118:121]
	v_mfma_f32_16x16x32_bf16 v[86:89], v[198:201], v[244:247], v[86:89]
	v_mfma_f32_16x16x32_bf16 v[54:57], v[198:201], v[248:251], v[54:57]
	ds_read_b128 v[224:227], v161 offset:15360
	v_mfma_f32_16x16x32_bf16 v[22:25], v[198:201], v[148:151], v[22:25]
	v_mfma_f32_16x16x32_bf16 v[114:117], v[202:205], v[240:243], v[114:117]
	v_mfma_f32_16x16x32_bf16 v[82:85], v[202:205], v[244:247], v[82:85]
	v_mfma_f32_16x16x32_bf16 v[50:53], v[202:205], v[248:251], v[50:53]
	v_mfma_f32_16x16x32_bf16 v[18:21], v[202:205], v[148:151], v[18:21]
	s_waitcnt lgkmcnt(0)
	s_waitcnt vmcnt(0)
	s_barrier
	v_mfma_f32_16x16x32_bf16 v[110:113], v[206:209], v[240:243], v[110:113]
	v_mfma_f32_16x16x32_bf16 v[78:81], v[206:209], v[244:247], v[78:81]
	v_mfma_f32_16x16x32_bf16 v[46:49], v[206:209], v[248:251], v[46:49]
	v_mfma_f32_16x16x32_bf16 v[14:17], v[206:209], v[148:151], v[14:17]
	v_mfma_f32_16x16x32_bf16 v[106:109], v[216:219], v[240:243], v[106:109]
	v_mfma_f32_16x16x32_bf16 v[74:77], v[216:219], v[244:247], v[74:77]
	v_mfma_f32_16x16x32_bf16 v[42:45], v[216:219], v[248:251], v[42:45]
	v_mfma_f32_16x16x32_bf16 v[10:13], v[216:219], v[148:151], v[10:13]
	v_mfma_f32_16x16x32_bf16 v[102:105], v[220:223], v[240:243], v[102:105]
	v_mfma_f32_16x16x32_bf16 v[70:73], v[220:223], v[244:247], v[70:73]
	v_mfma_f32_16x16x32_bf16 v[38:41], v[220:223], v[248:251], v[38:41]
	v_mfma_f32_16x16x32_bf16 v[6:9], v[220:223], v[148:151], v[6:9]
	v_mfma_f32_16x16x32_bf16 v[98:101], v[224:227], v[240:243], v[98:101]
	v_mfma_f32_16x16x32_bf16 v[62:65], v[224:227], v[244:247], v[62:65]
	v_mfma_f32_16x16x32_bf16 v[34:37], v[224:227], v[248:251], v[34:37]
	v_mfma_f32_16x16x32_bf16 v[2:5], v[224:227], v[148:151], v[2:5]
	s_nop 7
	s_nop 3
	s_cmp_lg_u64 s[16:17], 0
	s_mov_b32 s50, 0x19570000
	s_cselect_b32 s50, 0x15570000, s50
	s_add_u32 s50, s4, s50
	s_addc_u32 s51, s5, 0
	v_and_b32_e32 v200, 0xc0, v210
	v_and_b32_e32 v201, 15, v210
	v_or3_b32 v200, v138, v200, v201
	v_ashrrev_i32_e32 v201, 1, v210
	v_and_b32_e32 v201, 0xffffff80, v201
	v_add_u32_e32 v201, v201, v140
	v_lshlrev_b32_e32 v160, 11, v200
	v_lshl_add_u32 v160, v201, 1, v160
	v_bfe_u32 v205, v210, 4, 2
	v_and_b32_e32 v200, 1, v205
	v_lshl_add_u32 v160, v200, 5, v160
	v_lshrrev_b32_e32 v200, 1, v205
	v_lshl_add_u32 v160, v200, 4, v160
	v_add_u32_e32 v161, 0x8000, v160
	v_add_u32_e32 v163, 0x10000, v160
	v_add_u32_e32 v167, 0x18000, v160
	s_cmp_lg_u64 s[14:15], 0
	s_cbranch_scc1 .LeD_p1
; DI unsigned pk2(float lo, float hi) { f32x2 v = {lo, hi}; bf16x2_t b = __builtin_convertvector(v, bf16x2_t); return __builtin_bit_cast(unsigned, b); }
; DI float bflo(unsigned u) { return __uint_as_float(u << 16); }
; DI float bfhi(unsigned u) { return __uint_as_float(u & 0xffff0000u); }
; DI void phaseD(const Params& p0, const Slot sl, int layer, unsigned char* lds) {
;     ...
; #pragma unroll
;       for (int j = 0; j < 4; ++j) {
;         const long tok = (long)mt * 256 + wb * 64 + j * 16 + qi;
; #pragma unroll
;         for (int i = 0; i < 8; ++i) {
;           const long off = tok * 1024 + nt * 256 + wa * 128 + i * 16 + quad * 4;
;           const u32x2 xg = *(const u32x2*)(Gg + off);
;           const f32x4 v = acc[i][j];
;           float o0 = bflo(xg[0]) * v[0], o1 = bfhi(xg[0]) * v[1], o2 = bflo(xg[1]) * v[2], o3 = bfhi(xg[1]) * v[3];
;           if (which) { const u32x2 a = *(const u32x2*)(p.merged() + off); o0 += bflo(a[0]); o1 += bfhi(a[0]); o2 += bflo(a[1]); o3 += bfhi(a[1]); }
;           *(u32x2*)(p.merged() + off) = (u32x2){pk2(o0, o1), pk2(o2, o3)};
;           if ((i & 3) == 3) asm volatile("" ::: "memory");
	global_load_dwordx4 v[168:171], v160, s[50:51]
	global_load_dwordx4 v[172:175], v160, s[50:51] offset:64
	global_load_dwordx4 v[176:179], v160, s[50:51] offset:128
	global_load_dwordx4 v[180:183], v160, s[50:51] offset:192
	global_load_dwordx4 v[184:187], v161, s[50:51]
	global_load_dwordx4 v[188:191], v161, s[50:51] offset:64
	global_load_dwordx4 v[192:195], v161, s[50:51] offset:128
	global_load_dwordx4 v[196:199], v161, s[50:51] offset:192
	global_load_dwordx4 v[216:219], v163, s[50:51]
	global_load_dwordx4 v[220:223], v163, s[50:51] offset:64
	global_load_dwordx4 v[224:227], v163, s[50:51] offset:128
	global_load_dwordx4 v[240:243], v163, s[50:51] offset:192
	global_load_dwordx4 v[244:247], v167, s[50:51]
	global_load_dwordx4 v[248:251], v167, s[50:51] offset:64
	s_waitcnt vmcnt(13)
	v_permlane16_swap_b32_e32 v168, v170
	v_permlane16_swap_b32_e32 v169, v171
	v_lshlrev_b32_e32 v206, 16, v168
	v_and_b32_e32 v207, 0xffff0000, v168
	v_lshlrev_b32_e32 v208, 16, v169
	v_and_b32_e32 v209, 0xffff0000, v169
	v_pk_mul_f32 v[126:127], v[126:127], v[206:207]
	v_pk_mul_f32 v[128:129], v[128:129], v[208:209]
	v_lshlrev_b32_e32 v206, 16, v170
	v_and_b32_e32 v207, 0xffff0000, v170
	v_lshlrev_b32_e32 v208, 16, v171
	v_and_b32_e32 v209, 0xffff0000, v171
	v_pk_mul_f32 v[122:123], v[122:123], v[206:207]
	v_pk_mul_f32 v[124:125], v[124:125], v[208:209]
	global_load_dwordx4 v[168:171], v167, s[50:51] offset:128
	s_waitcnt vmcnt(13)
	v_permlane16_swap_b32_e32 v172, v174
	v_permlane16_swap_b32_e32 v173, v175
	v_lshlrev_b32_e32 v206, 16, v172
	v_and_b32_e32 v207, 0xffff0000, v172
	v_lshlrev_b32_e32 v208, 16, v173
	v_and_b32_e32 v209, 0xffff0000, v173
	v_pk_mul_f32 v[118:119], v[118:119], v[206:207]
	v_pk_mul_f32 v[120:121], v[120:121], v[208:209]
	v_lshlrev_b32_e32 v206, 16, v174
	v_and_b32_e32 v207, 0xffff0000, v174
	v_lshlrev_b32_e32 v208, 16, v175
	v_and_b32_e32 v209, 0xffff0000, v175
	v_pk_mul_f32 v[114:115], v[114:115], v[206:207]
	v_pk_mul_f32 v[116:117], v[116:117], v[208:209]
	global_load_dwordx4 v[172:175], v167, s[50:51] offset:192
	v_cvt_pk_bf16_f32 v152, v118, v119
	v_cvt_pk_bf16_f32 v153, v120, v121
	v_cvt_pk_bf16_f32 v154, v114, v115
	v_cvt_pk_bf16_f32 v155, v116, v117
	s_nop 1
	v_permlane16_swap_b32_e32 v152, v154
	v_permlane16_swap_b32_e32 v153, v155
	global_store_dwordx4 v160, v[152:155], s[10:11] offset:64
	v_cvt_pk_bf16_f32 v156, v126, v127
	v_cvt_pk_bf16_f32 v157, v128, v129
	v_cvt_pk_bf16_f32 v158, v122, v123
	v_cvt_pk_bf16_f32 v159, v124, v125
	s_nop 1
	v_permlane16_swap_b32_e32 v156, v158
	v_permlane16_swap_b32_e32 v157, v159
	global_store_dwordx4 v160, v[156:159], s[10:11]
	s_waitcnt vmcnt(15)
	v_permlane16_swap_b32_e32 v176, v178
	v_permlane16_swap_b32_e32 v177, v179
	v_lshlrev_b32_e32 v206, 16, v176
	v_and_b32_e32 v207, 0xffff0000, v176
	v_lshlrev_b32_e32 v208, 16, v177
	v_and_b32_e32 v209, 0xffff0000, v177
	v_pk_mul_f32 v[110:111], v[110:111], v[206:207]
	v_pk_mul_f32 v[112:113], v[112:113], v[208:209]
	v_lshlrev_b32_e32 v206, 16, v178
	v_and_b32_e32 v207, 0xffff0000, v178
	v_lshlrev_b32_e32 v208, 16, v179
	v_and_b32_e32 v209, 0xffff0000, v179
	v_pk_mul_f32 v[106:107], v[106:107], v[206:207]
	v_pk_mul_f32 v[108:109], v[108:109], v[208:209]
	v_cvt_pk_bf16_f32 v152, v110, v111
	v_cvt_pk_bf16_f32 v153, v112, v113
	v_cvt_pk_bf16_f32 v154, v106, v107
	v_cvt_pk_bf16_f32 v155, v108, v109
	s_nop 1
	v_permlane16_swap_b32_e32 v152, v154
	v_permlane16_swap_b32_e32 v153, v155
	global_store_dwordx4 v160, v[152:155], s[10:11] offset:128
	s_waitcnt vmcnt(15)
	v_permlane16_swap_b32_e32 v180, v182
	v_permlane16_swap_b32_e32 v181, v183
	v_lshlrev_b32_e32 v206, 16, v180
	v_and_b32_e32 v207, 0xffff0000, v180
	v_lshlrev_b32_e32 v208, 16, v181
	v_and_b32_e32 v209, 0xffff0000, v181
	v_pk_mul_f32 v[102:103], v[102:103], v[206:207]
	v_pk_mul_f32 v[104:105], v[104:105], v[208:209]
	v_lshlrev_b32_e32 v206, 16, v182
	v_and_b32_e32 v207, 0xffff0000, v182
	v_lshlrev_b32_e32 v208, 16, v183
	v_and_b32_e32 v209, 0xffff0000, v183
	v_pk_mul_f32 v[98:99], v[98:99], v[206:207]
	v_pk_mul_f32 v[100:101], v[100:101], v[208:209]
	v_cvt_pk_bf16_f32 v156, v102, v103
	v_cvt_pk_bf16_f32 v157, v104, v105
	v_cvt_pk_bf16_f32 v158, v98, v99
	v_cvt_pk_bf16_f32 v159, v100, v101
	s_nop 1
	v_permlane16_swap_b32_e32 v156, v158
	v_permlane16_swap_b32_e32 v157, v159
	global_store_dwordx4 v160, v[156:159], s[10:11] offset:192
	s_waitcnt vmcnt(15)
	v_permlane16_swap_b32_e32 v184, v186
	v_permlane16_swap_b32_e32 v185, v187
	v_lshlrev_b32_e32 v206, 16, v184
	v_and_b32_e32 v207, 0xffff0000, v184
	v_lshlrev_b32_e32 v208, 16, v185
	v_and_b32_e32 v209, 0xffff0000, v185
	v_pk_mul_f32 v[94:95], v[94:95], v[206:207]
	v_pk_mul_f32 v[96:97], v[96:97], v[208:209]
	v_lshlrev_b32_e32 v206, 16, v186
	v_and_b32_e32 v207, 0xffff0000, v186
	v_lshlrev_b32_e32 v208, 16, v187
	v_and_b32_e32 v209, 0xffff0000, v187
	v_pk_mul_f32 v[90:91], v[90:91], v[206:207]
	v_pk_mul_f32 v[92:93], v[92:93], v[208:209]
	v_cvt_pk_bf16_f32 v152, v94, v95
	v_cvt_pk_bf16_f32 v153, v96, v97
	v_cvt_pk_bf16_f32 v154, v90, v91
	v_cvt_pk_bf16_f32 v155, v92, v93
	s_nop 1
	v_permlane16_swap_b32_e32 v152, v154
	v_permlane16_swap_b32_e32 v153, v155
	global_store_dwordx4 v161, v[152:155], s[10:11]
	s_waitcnt vmcnt(15)
	v_permlane16_swap_b32_e32 v188, v190
	v_permlane16_swap_b32_e32 v189, v191
	v_lshlrev_b32_e32 v206, 16, v188
	v_and_b32_e32 v207, 0xffff0000, v188
	v_lshlrev_b32_e32 v208, 16, v189
	v_and_b32_e32 v209, 0xffff0000, v189
	v_pk_mul_f32 v[86:87], v[86:87], v[206:207]
	v_pk_mul_f32 v[88:89], v[88:89], v[208:209]
	v_lshlrev_b32_e32 v206, 16, v190
	v_and_b32_e32 v207, 0xffff0000, v190
	v_lshlrev_b32_e32 v208, 16, v191
	v_and_b32_e32 v209, 0xffff0000, v191
	v_pk_mul_f32 v[82:83], v[82:83], v[206:207]
	v_pk_mul_f32 v[84:85], v[84:85], v[208:209]
	v_cvt_pk_bf16_f32 v156, v86, v87
	v_cvt_pk_bf16_f32 v157, v88, v89
	v_cvt_pk_bf16_f32 v158, v82, v83
	v_cvt_pk_bf16_f32 v159, v84, v85
	s_nop 1
	v_permlane16_swap_b32_e32 v156, v158
	v_permlane16_swap_b32_e32 v157, v159
	global_store_dwordx4 v161, v[156:159], s[10:11] offset:64
	s_waitcnt vmcnt(15)
; DI unsigned pk2(float lo, float hi) { f32x2 v = {lo, hi}; bf16x2_t b = __builtin_convertvector(v, bf16x2_t); return __builtin_bit_cast(unsigned, b); }
; DI float bflo(unsigned u) { return __uint_as_float(u << 16); }
; DI float bfhi(unsigned u) { return __uint_as_float(u & 0xffff0000u); }
; DI void phaseD(const Params& p0, const Slot sl, int layer, unsigned char* lds) {
;     ...
; #pragma unroll
;       for (int j = 0; j < 4; ++j) {
;         const long tok = (long)mt * 256 + wb * 64 + j * 16 + qi;
; #pragma unroll
;         for (int i = 0; i < 8; ++i) {
;           const long off = tok * 1024 + nt * 256 + wa * 128 + i * 16 + quad * 4;
;           const u32x2 xg = *(const u32x2*)(Gg + off);
;           const f32x4 v = acc[i][j];
;           float o0 = bflo(xg[0]) * v[0], o1 = bfhi(xg[0]) * v[1], o2 = bflo(xg[1]) * v[2], o3 = bfhi(xg[1]) * v[3];
;           if (which) { const u32x2 a = *(const u32x2*)(p.merged() + off); o0 += bflo(a[0]); o1 += bfhi(a[0]); o2 += bflo(a[1]); o3 += bfhi(a[1]); }
;           *(u32x2*)(p.merged() + off) = (u32x2){pk2(o0, o1), pk2(o2, o3)};
;           if ((i & 3) == 3) asm volatile("" ::: "memory");
;         }
;       }
	v_permlane16_swap_b32_e32 v192, v194
	v_permlane16_swap_b32_e32 v193, v195
	v_lshlrev_b32_e32 v206, 16, v192
	v_and_b32_e32 v207, 0xffff0000, v192
	v_lshlrev_b32_e32 v208, 16, v193
	v_and_b32_e32 v209, 0xffff0000, v193
	v_pk_mul_f32 v[78:79], v[78:79], v[206:207]
	v_pk_mul_f32 v[80:81], v[80:81], v[208:209]
	v_lshlrev_b32_e32 v206, 16, v194
	v_and_b32_e32 v207, 0xffff0000, v194
	v_lshlrev_b32_e32 v208, 16, v195
	v_and_b32_e32 v209, 0xffff0000, v195
	v_pk_mul_f32 v[74:75], v[74:75], v[206:207]
	v_pk_mul_f32 v[76:77], v[76:77], v[208:209]
	v_cvt_pk_bf16_f32 v152, v78, v79
	v_cvt_pk_bf16_f32 v153, v80, v81
	v_cvt_pk_bf16_f32 v154, v74, v75
	v_cvt_pk_bf16_f32 v155, v76, v77
	s_nop 1
	v_permlane16_swap_b32_e32 v152, v154
	v_permlane16_swap_b32_e32 v153, v155
	global_store_dwordx4 v161, v[152:155], s[10:11] offset:128
	s_waitcnt vmcnt(15)
	v_permlane16_swap_b32_e32 v196, v198
	v_permlane16_swap_b32_e32 v197, v199
	v_lshlrev_b32_e32 v206, 16, v196
	v_and_b32_e32 v207, 0xffff0000, v196
	v_lshlrev_b32_e32 v208, 16, v197
	v_and_b32_e32 v209, 0xffff0000, v197
	v_pk_mul_f32 v[70:71], v[70:71], v[206:207]
	v_pk_mul_f32 v[72:73], v[72:73], v[208:209]
	v_lshlrev_b32_e32 v206, 16, v198
	v_and_b32_e32 v207, 0xffff0000, v198
	v_lshlrev_b32_e32 v208, 16, v199
	v_and_b32_e32 v209, 0xffff0000, v199
	v_pk_mul_f32 v[62:63], v[62:63], v[206:207]
	v_pk_mul_f32 v[64:65], v[64:65], v[208:209]
	v_cvt_pk_bf16_f32 v156, v70, v71
	v_cvt_pk_bf16_f32 v157, v72, v73
	v_cvt_pk_bf16_f32 v158, v62, v63
	v_cvt_pk_bf16_f32 v159, v64, v65
	s_nop 1
	v_permlane16_swap_b32_e32 v156, v158
	v_permlane16_swap_b32_e32 v157, v159
	global_store_dwordx4 v161, v[156:159], s[10:11] offset:192
	s_waitcnt vmcnt(15)
	v_permlane16_swap_b32_e32 v216, v218
	v_permlane16_swap_b32_e32 v217, v219
	v_lshlrev_b32_e32 v206, 16, v216
	v_and_b32_e32 v207, 0xffff0000, v216
	v_lshlrev_b32_e32 v208, 16, v217
	v_and_b32_e32 v209, 0xffff0000, v217
	v_pk_mul_f32 v[66:67], v[66:67], v[206:207]
	v_pk_mul_f32 v[68:69], v[68:69], v[208:209]
	v_lshlrev_b32_e32 v206, 16, v218
	v_and_b32_e32 v207, 0xffff0000, v218
	v_lshlrev_b32_e32 v208, 16, v219
	v_and_b32_e32 v209, 0xffff0000, v219
	v_pk_mul_f32 v[58:59], v[58:59], v[206:207]
	v_pk_mul_f32 v[60:61], v[60:61], v[208:209]
	v_cvt_pk_bf16_f32 v152, v66, v67
	v_cvt_pk_bf16_f32 v153, v68, v69
	v_cvt_pk_bf16_f32 v154, v58, v59
	v_cvt_pk_bf16_f32 v155, v60, v61
	s_nop 1
	v_permlane16_swap_b32_e32 v152, v154
	v_permlane16_swap_b32_e32 v153, v155
	global_store_dwordx4 v163, v[152:155], s[10:11]
	s_waitcnt vmcnt(15)
	v_permlane16_swap_b32_e32 v220, v222
	v_permlane16_swap_b32_e32 v221, v223
	v_lshlrev_b32_e32 v206, 16, v220
	v_and_b32_e32 v207, 0xffff0000, v220
	v_lshlrev_b32_e32 v208, 16, v221
	v_and_b32_e32 v209, 0xffff0000, v221
	v_pk_mul_f32 v[54:55], v[54:55], v[206:207]
	v_pk_mul_f32 v[56:57], v[56:57], v[208:209]
	v_lshlrev_b32_e32 v206, 16, v222
	v_and_b32_e32 v207, 0xffff0000, v222
	v_lshlrev_b32_e32 v208, 16, v223
	v_and_b32_e32 v209, 0xffff0000, v223
	v_pk_mul_f32 v[50:51], v[50:51], v[206:207]
	v_pk_mul_f32 v[52:53], v[52:53], v[208:209]
	v_cvt_pk_bf16_f32 v156, v54, v55
	v_cvt_pk_bf16_f32 v157, v56, v57
	v_cvt_pk_bf16_f32 v158, v50, v51
	v_cvt_pk_bf16_f32 v159, v52, v53
	s_nop 1
	v_permlane16_swap_b32_e32 v156, v158
	v_permlane16_swap_b32_e32 v157, v159
	global_store_dwordx4 v163, v[156:159], s[10:11] offset:64
	s_waitcnt vmcnt(15)
	v_permlane16_swap_b32_e32 v224, v226
	v_permlane16_swap_b32_e32 v225, v227
	v_lshlrev_b32_e32 v206, 16, v224
	v_and_b32_e32 v207, 0xffff0000, v224
	v_lshlrev_b32_e32 v208, 16, v225
	v_and_b32_e32 v209, 0xffff0000, v225
	v_pk_mul_f32 v[46:47], v[46:47], v[206:207]
	v_pk_mul_f32 v[48:49], v[48:49], v[208:209]
	v_lshlrev_b32_e32 v206, 16, v226
	v_and_b32_e32 v207, 0xffff0000, v226
	v_lshlrev_b32_e32 v208, 16, v227
	v_and_b32_e32 v209, 0xffff0000, v227
	v_pk_mul_f32 v[42:43], v[42:43], v[206:207]
	v_pk_mul_f32 v[44:45], v[44:45], v[208:209]
	v_cvt_pk_bf16_f32 v152, v46, v47
	v_cvt_pk_bf16_f32 v153, v48, v49
	v_cvt_pk_bf16_f32 v154, v42, v43
	v_cvt_pk_bf16_f32 v155, v44, v45
	s_nop 1
	v_permlane16_swap_b32_e32 v152, v154
	v_permlane16_swap_b32_e32 v153, v155
	global_store_dwordx4 v163, v[152:155], s[10:11] offset:128
	s_waitcnt vmcnt(15)
	v_permlane16_swap_b32_e32 v240, v242
	v_permlane16_swap_b32_e32 v241, v243
	v_lshlrev_b32_e32 v206, 16, v240
	v_and_b32_e32 v207, 0xffff0000, v240
	v_lshlrev_b32_e32 v208, 16, v241
	v_and_b32_e32 v209, 0xffff0000, v241
	v_pk_mul_f32 v[38:39], v[38:39], v[206:207]
	v_pk_mul_f32 v[40:41], v[40:41], v[208:209]
	v_lshlrev_b32_e32 v206, 16, v242
	v_and_b32_e32 v207, 0xffff0000, v242
	v_lshlrev_b32_e32 v208, 16, v243
	v_and_b32_e32 v209, 0xffff0000, v243
	v_pk_mul_f32 v[34:35], v[34:35], v[206:207]
	v_pk_mul_f32 v[36:37], v[36:37], v[208:209]
	v_cvt_pk_bf16_f32 v156, v38, v39
	v_cvt_pk_bf16_f32 v157, v40, v41
	v_cvt_pk_bf16_f32 v158, v34, v35
	v_cvt_pk_bf16_f32 v159, v36, v37
	s_nop 1
	v_permlane16_swap_b32_e32 v156, v158
	v_permlane16_swap_b32_e32 v157, v159
	global_store_dwordx4 v163, v[156:159], s[10:11] offset:192
	s_waitcnt vmcnt(15)
	v_permlane16_swap_b32_e32 v244, v246
	v_permlane16_swap_b32_e32 v245, v247
	v_lshlrev_b32_e32 v206, 16, v244
	v_and_b32_e32 v207, 0xffff0000, v244
	v_lshlrev_b32_e32 v208, 16, v245
	v_and_b32_e32 v209, 0xffff0000, v245
	v_pk_mul_f32 v[30:31], v[30:31], v[206:207]
	v_pk_mul_f32 v[32:33], v[32:33], v[208:209]
	v_lshlrev_b32_e32 v206, 16, v246
	v_and_b32_e32 v207, 0xffff0000, v246
	v_lshlrev_b32_e32 v208, 16, v247
	v_and_b32_e32 v209, 0xffff0000, v247
	v_pk_mul_f32 v[26:27], v[26:27], v[206:207]
	v_pk_mul_f32 v[28:29], v[28:29], v[208:209]
	v_cvt_pk_bf16_f32 v152, v30, v31
	v_cvt_pk_bf16_f32 v153, v32, v33
	v_cvt_pk_bf16_f32 v154, v26, v27
	v_cvt_pk_bf16_f32 v155, v28, v29
	s_nop 1
	v_permlane16_swap_b32_e32 v152, v154
	v_permlane16_swap_b32_e32 v153, v155
	global_store_dwordx4 v167, v[152:155], s[10:11]
	s_waitcnt vmcnt(15)
; DI unsigned pk2(float lo, float hi) { f32x2 v = {lo, hi}; bf16x2_t b = __builtin_convertvector(v, bf16x2_t); return __builtin_bit_cast(unsigned, b); }
; DI float bflo(unsigned u) { return __uint_as_float(u << 16); }
; DI float bfhi(unsigned u) { return __uint_as_float(u & 0xffff0000u); }
; DI void phaseD(const Params& p0, const Slot sl, int layer, unsigned char* lds) {
;     ...
; #pragma unroll
;       for (int j = 0; j < 4; ++j) {
;         const long tok = (long)mt * 256 + wb * 64 + j * 16 + qi;
; #pragma unroll
;         for (int i = 0; i < 8; ++i) {
;           const long off = tok * 1024 + nt * 256 + wa * 128 + i * 16 + quad * 4;
;           const u32x2 xg = *(const u32x2*)(Gg + off);
;           const f32x4 v = acc[i][j];
;           float o0 = bflo(xg[0]) * v[0], o1 = bfhi(xg[0]) * v[1], o2 = bflo(xg[1]) * v[2], o3 = bfhi(xg[1]) * v[3];
;           if (which) { const u32x2 a = *(const u32x2*)(p.merged() + off); o0 += bflo(a[0]); o1 += bfhi(a[0]); o2 += bflo(a[1]); o3 += bfhi(a[1]); }
;           *(u32x2*)(p.merged() + off) = (u32x2){pk2(o0, o1), pk2(o2, o3)};
;           if ((i & 3) == 3) asm volatile("" ::: "memory");
;         }
;       }
	v_permlane16_swap_b32_e32 v248, v250
	v_permlane16_swap_b32_e32 v249, v251
	v_lshlrev_b32_e32 v206, 16, v248
	v_and_b32_e32 v207, 0xffff0000, v248
	v_lshlrev_b32_e32 v208, 16, v249
	v_and_b32_e32 v209, 0xffff0000, v249
	v_pk_mul_f32 v[22:23], v[22:23], v[206:207]
	v_pk_mul_f32 v[24:25], v[24:25], v[208:209]
	v_lshlrev_b32_e32 v206, 16, v250
	v_and_b32_e32 v207, 0xffff0000, v250
	v_lshlrev_b32_e32 v208, 16, v251
	v_and_b32_e32 v209, 0xffff0000, v251
	v_pk_mul_f32 v[18:19], v[18:19], v[206:207]
	v_pk_mul_f32 v[20:21], v[20:21], v[208:209]
	v_cvt_pk_bf16_f32 v156, v22, v23
	v_cvt_pk_bf16_f32 v157, v24, v25
	v_cvt_pk_bf16_f32 v158, v18, v19
	v_cvt_pk_bf16_f32 v159, v20, v21
	s_nop 1
	v_permlane16_swap_b32_e32 v156, v158
	v_permlane16_swap_b32_e32 v157, v159
	global_store_dwordx4 v167, v[156:159], s[10:11] offset:64
	s_waitcnt vmcnt(15)
	v_permlane16_swap_b32_e32 v168, v170
	v_permlane16_swap_b32_e32 v169, v171
	v_lshlrev_b32_e32 v206, 16, v168
	v_and_b32_e32 v207, 0xffff0000, v168
	v_lshlrev_b32_e32 v208, 16, v169
	v_and_b32_e32 v209, 0xffff0000, v169
	v_pk_mul_f32 v[14:15], v[14:15], v[206:207]
	v_pk_mul_f32 v[16:17], v[16:17], v[208:209]
	v_lshlrev_b32_e32 v206, 16, v170
	v_and_b32_e32 v207, 0xffff0000, v170
	v_lshlrev_b32_e32 v208, 16, v171
	v_and_b32_e32 v209, 0xffff0000, v171
	v_pk_mul_f32 v[10:11], v[10:11], v[206:207]
	v_pk_mul_f32 v[12:13], v[12:13], v[208:209]
	v_cvt_pk_bf16_f32 v152, v14, v15
	v_cvt_pk_bf16_f32 v153, v16, v17
	v_cvt_pk_bf16_f32 v154, v10, v11
	v_cvt_pk_bf16_f32 v155, v12, v13
	s_nop 1
	v_permlane16_swap_b32_e32 v152, v154
	v_permlane16_swap_b32_e32 v153, v155
	global_store_dwordx4 v167, v[152:155], s[10:11] offset:128
	s_waitcnt vmcnt(15)
	v_permlane16_swap_b32_e32 v172, v174
	v_permlane16_swap_b32_e32 v173, v175
	v_lshlrev_b32_e32 v206, 16, v172
	v_and_b32_e32 v207, 0xffff0000, v172
	v_lshlrev_b32_e32 v208, 16, v173
	v_and_b32_e32 v209, 0xffff0000, v173
	v_pk_mul_f32 v[6:7], v[6:7], v[206:207]
	v_pk_mul_f32 v[8:9], v[8:9], v[208:209]
	v_lshlrev_b32_e32 v206, 16, v174
	v_and_b32_e32 v207, 0xffff0000, v174
	v_lshlrev_b32_e32 v208, 16, v175
	v_and_b32_e32 v209, 0xffff0000, v175
	v_pk_mul_f32 v[2:3], v[2:3], v[206:207]
	v_pk_mul_f32 v[4:5], v[4:5], v[208:209]
	v_cvt_pk_bf16_f32 v156, v6, v7
	v_cvt_pk_bf16_f32 v157, v8, v9
	v_cvt_pk_bf16_f32 v158, v2, v3
	v_cvt_pk_bf16_f32 v159, v4, v5
	s_nop 1
	v_permlane16_swap_b32_e32 v156, v158
	v_permlane16_swap_b32_e32 v157, v159
	global_store_dwordx4 v167, v[156:159], s[10:11] offset:192
	s_branch .Lmy_D_cont
.LeD_p1:
	global_load_dwordx4 v[168:171], v160, s[50:51]
	global_load_dwordx4 v[172:175], v160, s[10:11]
	global_load_dwordx4 v[176:179], v160, s[50:51] offset:64
	global_load_dwordx4 v[180:183], v160, s[10:11] offset:64
	global_load_dwordx4 v[184:187], v160, s[50:51] offset:128
	global_load_dwordx4 v[188:191], v160, s[10:11] offset:128
	global_load_dwordx4 v[192:195], v160, s[50:51] offset:192
	global_load_dwordx4 v[196:199], v160, s[10:11] offset:192
	global_load_dwordx4 v[216:219], v161, s[50:51]
	global_load_dwordx4 v[220:223], v161, s[10:11]
	global_load_dwordx4 v[224:227], v161, s[50:51] offset:64
	global_load_dwordx4 v[240:243], v161, s[10:11] offset:64
	global_load_dwordx4 v[244:247], v161, s[50:51] offset:128
	global_load_dwordx4 v[248:251], v161, s[10:11] offset:128
	s_waitcnt vmcnt(12)
	v_permlane16_swap_b32_e32 v168, v170
	v_permlane16_swap_b32_e32 v169, v171
	v_permlane16_swap_b32_e32 v172, v174
	v_permlane16_swap_b32_e32 v173, v175
	v_lshlrev_b32_e32 v206, 16, v168
	v_and_b32_e32 v207, 0xffff0000, v168
	v_lshlrev_b32_e32 v208, 16, v169
	v_and_b32_e32 v209, 0xffff0000, v169
	v_pk_mul_f32 v[126:127], v[126:127], v[206:207]
	v_pk_mul_f32 v[128:129], v[128:129], v[208:209]
	v_lshlrev_b32_e32 v206, 16, v170
	v_and_b32_e32 v207, 0xffff0000, v170
	v_lshlrev_b32_e32 v208, 16, v171
	v_and_b32_e32 v209, 0xffff0000, v171
	v_pk_mul_f32 v[122:123], v[122:123], v[206:207]
	v_pk_mul_f32 v[124:125], v[124:125], v[208:209]
	v_lshlrev_b32_e32 v206, 16, v172
	v_and_b32_e32 v207, 0xffff0000, v172
	v_lshlrev_b32_e32 v208, 16, v173
	v_and_b32_e32 v209, 0xffff0000, v173
	v_pk_add_f32 v[126:127], v[126:127], v[206:207]
	v_pk_add_f32 v[128:129], v[128:129], v[208:209]
	v_lshlrev_b32_e32 v206, 16, v174
	v_and_b32_e32 v207, 0xffff0000, v174
	v_lshlrev_b32_e32 v208, 16, v175
	v_and_b32_e32 v209, 0xffff0000, v175
	v_pk_add_f32 v[122:123], v[122:123], v[206:207]
	v_pk_add_f32 v[124:125], v[124:125], v[208:209]
	global_load_dwordx4 v[168:171], v161, s[50:51] offset:192
	global_load_dwordx4 v[172:175], v161, s[10:11] offset:192
	s_waitcnt vmcnt(12)
	v_permlane16_swap_b32_e32 v176, v178
	v_permlane16_swap_b32_e32 v177, v179
	v_permlane16_swap_b32_e32 v180, v182
	v_permlane16_swap_b32_e32 v181, v183
	v_lshlrev_b32_e32 v206, 16, v176
	v_and_b32_e32 v207, 0xffff0000, v176
	v_lshlrev_b32_e32 v208, 16, v177
	v_and_b32_e32 v209, 0xffff0000, v177
	v_pk_mul_f32 v[118:119], v[118:119], v[206:207]
	v_pk_mul_f32 v[120:121], v[120:121], v[208:209]
	v_lshlrev_b32_e32 v206, 16, v178
	v_and_b32_e32 v207, 0xffff0000, v178
	v_lshlrev_b32_e32 v208, 16, v179
	v_and_b32_e32 v209, 0xffff0000, v179
	v_pk_mul_f32 v[114:115], v[114:115], v[206:207]
	v_pk_mul_f32 v[116:117], v[116:117], v[208:209]
	v_lshlrev_b32_e32 v206, 16, v180
	v_and_b32_e32 v207, 0xffff0000, v180
	v_lshlrev_b32_e32 v208, 16, v181
	v_and_b32_e32 v209, 0xffff0000, v181
	v_pk_add_f32 v[118:119], v[118:119], v[206:207]
	v_pk_add_f32 v[120:121], v[120:121], v[208:209]
	v_lshlrev_b32_e32 v206, 16, v182
	v_and_b32_e32 v207, 0xffff0000, v182
	v_lshlrev_b32_e32 v208, 16, v183
	v_and_b32_e32 v209, 0xffff0000, v183
	v_pk_add_f32 v[114:115], v[114:115], v[206:207]
	v_pk_add_f32 v[116:117], v[116:117], v[208:209]
	global_load_dwordx4 v[176:179], v163, s[50:51]
	global_load_dwordx4 v[180:183], v163, s[10:11]
	s_waitcnt vmcnt(12)
; DI unsigned pk2(float lo, float hi) { f32x2 v = {lo, hi}; bf16x2_t b = __builtin_convertvector(v, bf16x2_t); return __builtin_bit_cast(unsigned, b); }
; DI float bflo(unsigned u) { return __uint_as_float(u << 16); }
; DI float bfhi(unsigned u) { return __uint_as_float(u & 0xffff0000u); }
; DI void phaseD(const Params& p0, const Slot sl, int layer, unsigned char* lds) {
;     ...
; #pragma unroll
;       for (int j = 0; j < 4; ++j) {
;         const long tok = (long)mt * 256 + wb * 64 + j * 16 + qi;
; #pragma unroll
;         for (int i = 0; i < 8; ++i) {
;           const long off = tok * 1024 + nt * 256 + wa * 128 + i * 16 + quad * 4;
;           const u32x2 xg = *(const u32x2*)(Gg + off);
;           const f32x4 v = acc[i][j];
;           float o0 = bflo(xg[0]) * v[0], o1 = bfhi(xg[0]) * v[1], o2 = bflo(xg[1]) * v[2], o3 = bfhi(xg[1]) * v[3];
;           if (which) { const u32x2 a = *(const u32x2*)(p.merged() + off); o0 += bflo(a[0]); o1 += bfhi(a[0]); o2 += bflo(a[1]); o3 += bfhi(a[1]); }
;           *(u32x2*)(p.merged() + off) = (u32x2){pk2(o0, o1), pk2(o2, o3)};
;           if ((i & 3) == 3) asm volatile("" ::: "memory");
;         }
;       }
	v_permlane16_swap_b32_e32 v184, v186
	v_permlane16_swap_b32_e32 v185, v187
	v_permlane16_swap_b32_e32 v188, v190
	v_permlane16_swap_b32_e32 v189, v191
	v_lshlrev_b32_e32 v206, 16, v184
	v_and_b32_e32 v207, 0xffff0000, v184
	v_lshlrev_b32_e32 v208, 16, v185
	v_and_b32_e32 v209, 0xffff0000, v185
	v_pk_mul_f32 v[110:111], v[110:111], v[206:207]
	v_pk_mul_f32 v[112:113], v[112:113], v[208:209]
	v_lshlrev_b32_e32 v206, 16, v186
	v_and_b32_e32 v207, 0xffff0000, v186
	v_lshlrev_b32_e32 v208, 16, v187
	v_and_b32_e32 v209, 0xffff0000, v187
	v_pk_mul_f32 v[106:107], v[106:107], v[206:207]
	v_pk_mul_f32 v[108:109], v[108:109], v[208:209]
	v_lshlrev_b32_e32 v206, 16, v188
	v_and_b32_e32 v207, 0xffff0000, v188
	v_lshlrev_b32_e32 v208, 16, v189
	v_and_b32_e32 v209, 0xffff0000, v189
	v_pk_add_f32 v[110:111], v[110:111], v[206:207]
	v_pk_add_f32 v[112:113], v[112:113], v[208:209]
	v_lshlrev_b32_e32 v206, 16, v190
	v_and_b32_e32 v207, 0xffff0000, v190
	v_lshlrev_b32_e32 v208, 16, v191
	v_and_b32_e32 v209, 0xffff0000, v191
	v_pk_add_f32 v[106:107], v[106:107], v[206:207]
	v_pk_add_f32 v[108:109], v[108:109], v[208:209]
	global_load_dwordx4 v[184:187], v163, s[50:51] offset:64
	global_load_dwordx4 v[188:191], v163, s[10:11] offset:64
	s_waitcnt vmcnt(12)
	v_permlane16_swap_b32_e32 v192, v194
	v_permlane16_swap_b32_e32 v193, v195
	v_permlane16_swap_b32_e32 v196, v198
	v_permlane16_swap_b32_e32 v197, v199
	v_lshlrev_b32_e32 v206, 16, v192
	v_and_b32_e32 v207, 0xffff0000, v192
	v_lshlrev_b32_e32 v208, 16, v193
	v_and_b32_e32 v209, 0xffff0000, v193
	v_pk_mul_f32 v[102:103], v[102:103], v[206:207]
	v_pk_mul_f32 v[104:105], v[104:105], v[208:209]
	v_lshlrev_b32_e32 v206, 16, v194
	v_and_b32_e32 v207, 0xffff0000, v194
	v_lshlrev_b32_e32 v208, 16, v195
	v_and_b32_e32 v209, 0xffff0000, v195
	v_pk_mul_f32 v[98:99], v[98:99], v[206:207]
	v_pk_mul_f32 v[100:101], v[100:101], v[208:209]
	v_lshlrev_b32_e32 v206, 16, v196
	v_and_b32_e32 v207, 0xffff0000, v196
	v_lshlrev_b32_e32 v208, 16, v197
	v_and_b32_e32 v209, 0xffff0000, v197
	v_pk_add_f32 v[102:103], v[102:103], v[206:207]
	v_pk_add_f32 v[104:105], v[104:105], v[208:209]
	v_lshlrev_b32_e32 v206, 16, v198
	v_and_b32_e32 v207, 0xffff0000, v198
	v_lshlrev_b32_e32 v208, 16, v199
	v_and_b32_e32 v209, 0xffff0000, v199
	v_pk_add_f32 v[98:99], v[98:99], v[206:207]
	v_pk_add_f32 v[100:101], v[100:101], v[208:209]
	global_load_dwordx4 v[192:195], v163, s[50:51] offset:128
	global_load_dwordx4 v[196:199], v163, s[10:11] offset:128
	s_waitcnt vmcnt(12)
	v_permlane16_swap_b32_e32 v216, v218
	v_permlane16_swap_b32_e32 v217, v219
	v_permlane16_swap_b32_e32 v220, v222
	v_permlane16_swap_b32_e32 v221, v223
	v_lshlrev_b32_e32 v206, 16, v216
	v_and_b32_e32 v207, 0xffff0000, v216
	v_lshlrev_b32_e32 v208, 16, v217
	v_and_b32_e32 v209, 0xffff0000, v217
	v_pk_mul_f32 v[94:95], v[94:95], v[206:207]
	v_pk_mul_f32 v[96:97], v[96:97], v[208:209]
	v_lshlrev_b32_e32 v206, 16, v218
	v_and_b32_e32 v207, 0xffff0000, v218
	v_lshlrev_b32_e32 v208, 16, v219
	v_and_b32_e32 v209, 0xffff0000, v219
	v_pk_mul_f32 v[90:91], v[90:91], v[206:207]
	v_pk_mul_f32 v[92:93], v[92:93], v[208:209]
	v_lshlrev_b32_e32 v206, 16, v220
	v_and_b32_e32 v207, 0xffff0000, v220
	v_lshlrev_b32_e32 v208, 16, v221
	v_and_b32_e32 v209, 0xffff0000, v221
	v_pk_add_f32 v[94:95], v[94:95], v[206:207]
	v_pk_add_f32 v[96:97], v[96:97], v[208:209]
	v_lshlrev_b32_e32 v206, 16, v222
	v_and_b32_e32 v207, 0xffff0000, v222
	v_lshlrev_b32_e32 v208, 16, v223
	v_and_b32_e32 v209, 0xffff0000, v223
	v_pk_add_f32 v[90:91], v[90:91], v[206:207]
	v_pk_add_f32 v[92:93], v[92:93], v[208:209]
	global_load_dwordx4 v[216:219], v163, s[50:51] offset:192
	global_load_dwordx4 v[220:223], v163, s[10:11] offset:192
	s_waitcnt vmcnt(12)
	v_permlane16_swap_b32_e32 v224, v226
	v_permlane16_swap_b32_e32 v225, v227
	v_permlane16_swap_b32_e32 v240, v242
	v_permlane16_swap_b32_e32 v241, v243
	v_lshlrev_b32_e32 v206, 16, v224
	v_and_b32_e32 v207, 0xffff0000, v224
	v_lshlrev_b32_e32 v208, 16, v225
	v_and_b32_e32 v209, 0xffff0000, v225
	v_pk_mul_f32 v[86:87], v[86:87], v[206:207]
	v_pk_mul_f32 v[88:89], v[88:89], v[208:209]
	v_lshlrev_b32_e32 v206, 16, v226
	v_and_b32_e32 v207, 0xffff0000, v226
	v_lshlrev_b32_e32 v208, 16, v227
	v_and_b32_e32 v209, 0xffff0000, v227
	v_pk_mul_f32 v[82:83], v[82:83], v[206:207]
	v_pk_mul_f32 v[84:85], v[84:85], v[208:209]
	v_lshlrev_b32_e32 v206, 16, v240
	v_and_b32_e32 v207, 0xffff0000, v240
	v_lshlrev_b32_e32 v208, 16, v241
	v_and_b32_e32 v209, 0xffff0000, v241
	v_pk_add_f32 v[86:87], v[86:87], v[206:207]
	v_pk_add_f32 v[88:89], v[88:89], v[208:209]
	v_lshlrev_b32_e32 v206, 16, v242
	v_and_b32_e32 v207, 0xffff0000, v242
	v_lshlrev_b32_e32 v208, 16, v243
	v_and_b32_e32 v209, 0xffff0000, v243
	v_pk_add_f32 v[82:83], v[82:83], v[206:207]
	v_pk_add_f32 v[84:85], v[84:85], v[208:209]
	global_load_dwordx4 v[224:227], v167, s[50:51]
	global_load_dwordx4 v[240:243], v167, s[10:11]
	s_waitcnt vmcnt(12)
	v_permlane16_swap_b32_e32 v244, v246
	v_permlane16_swap_b32_e32 v245, v247
	v_permlane16_swap_b32_e32 v248, v250
	v_permlane16_swap_b32_e32 v249, v251
	v_lshlrev_b32_e32 v206, 16, v244
	v_and_b32_e32 v207, 0xffff0000, v244
	v_lshlrev_b32_e32 v208, 16, v245
	v_and_b32_e32 v209, 0xffff0000, v245
	v_pk_mul_f32 v[78:79], v[78:79], v[206:207]
	v_pk_mul_f32 v[80:81], v[80:81], v[208:209]
	v_lshlrev_b32_e32 v206, 16, v246
	v_and_b32_e32 v207, 0xffff0000, v246
	v_lshlrev_b32_e32 v208, 16, v247
	v_and_b32_e32 v209, 0xffff0000, v247
	v_pk_mul_f32 v[74:75], v[74:75], v[206:207]
	v_pk_mul_f32 v[76:77], v[76:77], v[208:209]
	v_lshlrev_b32_e32 v206, 16, v248
	v_and_b32_e32 v207, 0xffff0000, v248
	v_lshlrev_b32_e32 v208, 16, v249
	v_and_b32_e32 v209, 0xffff0000, v249
	v_pk_add_f32 v[78:79], v[78:79], v[206:207]
	v_pk_add_f32 v[80:81], v[80:81], v[208:209]
	v_lshlrev_b32_e32 v206, 16, v250
	v_and_b32_e32 v207, 0xffff0000, v250
	v_lshlrev_b32_e32 v208, 16, v251
	v_and_b32_e32 v209, 0xffff0000, v251
	v_pk_add_f32 v[74:75], v[74:75], v[206:207]
	v_pk_add_f32 v[76:77], v[76:77], v[208:209]
	global_load_dwordx4 v[244:247], v167, s[50:51] offset:64
	global_load_dwordx4 v[248:251], v167, s[10:11] offset:64
	s_waitcnt vmcnt(12)
; DI unsigned pk2(float lo, float hi) { f32x2 v = {lo, hi}; bf16x2_t b = __builtin_convertvector(v, bf16x2_t); return __builtin_bit_cast(unsigned, b); }
; DI float bflo(unsigned u) { return __uint_as_float(u << 16); }
; DI float bfhi(unsigned u) { return __uint_as_float(u & 0xffff0000u); }
; DI void phaseD(const Params& p0, const Slot sl, int layer, unsigned char* lds) {
;     ...
; #pragma unroll
;       for (int j = 0; j < 4; ++j) {
;         const long tok = (long)mt * 256 + wb * 64 + j * 16 + qi;
; #pragma unroll
;         for (int i = 0; i < 8; ++i) {
;           const long off = tok * 1024 + nt * 256 + wa * 128 + i * 16 + quad * 4;
;           const u32x2 xg = *(const u32x2*)(Gg + off);
;           const f32x4 v = acc[i][j];
;           float o0 = bflo(xg[0]) * v[0], o1 = bfhi(xg[0]) * v[1], o2 = bflo(xg[1]) * v[2], o3 = bfhi(xg[1]) * v[3];
;           if (which) { const u32x2 a = *(const u32x2*)(p.merged() + off); o0 += bflo(a[0]); o1 += bfhi(a[0]); o2 += bflo(a[1]); o3 += bfhi(a[1]); }
;           *(u32x2*)(p.merged() + off) = (u32x2){pk2(o0, o1), pk2(o2, o3)};
;           if ((i & 3) == 3) asm volatile("" ::: "memory");
;         }
;       }
	v_permlane16_swap_b32_e32 v168, v170
	v_permlane16_swap_b32_e32 v169, v171
	v_permlane16_swap_b32_e32 v172, v174
	v_permlane16_swap_b32_e32 v173, v175
	v_lshlrev_b32_e32 v206, 16, v168
	v_and_b32_e32 v207, 0xffff0000, v168
	v_lshlrev_b32_e32 v208, 16, v169
	v_and_b32_e32 v209, 0xffff0000, v169
	v_pk_mul_f32 v[70:71], v[70:71], v[206:207]
	v_pk_mul_f32 v[72:73], v[72:73], v[208:209]
	v_lshlrev_b32_e32 v206, 16, v170
	v_and_b32_e32 v207, 0xffff0000, v170
	v_lshlrev_b32_e32 v208, 16, v171
	v_and_b32_e32 v209, 0xffff0000, v171
	v_pk_mul_f32 v[62:63], v[62:63], v[206:207]
	v_pk_mul_f32 v[64:65], v[64:65], v[208:209]
	v_lshlrev_b32_e32 v206, 16, v172
	v_and_b32_e32 v207, 0xffff0000, v172
	v_lshlrev_b32_e32 v208, 16, v173
	v_and_b32_e32 v209, 0xffff0000, v173
	v_pk_add_f32 v[70:71], v[70:71], v[206:207]
	v_pk_add_f32 v[72:73], v[72:73], v[208:209]
	v_lshlrev_b32_e32 v206, 16, v174
	v_and_b32_e32 v207, 0xffff0000, v174
	v_lshlrev_b32_e32 v208, 16, v175
	v_and_b32_e32 v209, 0xffff0000, v175
	v_pk_add_f32 v[62:63], v[62:63], v[206:207]
	v_pk_add_f32 v[64:65], v[64:65], v[208:209]
	global_load_dwordx4 v[168:171], v167, s[50:51] offset:128
	global_load_dwordx4 v[172:175], v167, s[10:11] offset:128
	s_waitcnt vmcnt(12)
	v_permlane16_swap_b32_e32 v176, v178
	v_permlane16_swap_b32_e32 v177, v179
	v_permlane16_swap_b32_e32 v180, v182
	v_permlane16_swap_b32_e32 v181, v183
	v_lshlrev_b32_e32 v206, 16, v176
	v_and_b32_e32 v207, 0xffff0000, v176
	v_lshlrev_b32_e32 v208, 16, v177
	v_and_b32_e32 v209, 0xffff0000, v177
	v_pk_mul_f32 v[66:67], v[66:67], v[206:207]
	v_pk_mul_f32 v[68:69], v[68:69], v[208:209]
	v_lshlrev_b32_e32 v206, 16, v178
	v_and_b32_e32 v207, 0xffff0000, v178
	v_lshlrev_b32_e32 v208, 16, v179
	v_and_b32_e32 v209, 0xffff0000, v179
	v_pk_mul_f32 v[58:59], v[58:59], v[206:207]
	v_pk_mul_f32 v[60:61], v[60:61], v[208:209]
	v_lshlrev_b32_e32 v206, 16, v180
	v_and_b32_e32 v207, 0xffff0000, v180
	v_lshlrev_b32_e32 v208, 16, v181
	v_and_b32_e32 v209, 0xffff0000, v181
	v_pk_add_f32 v[66:67], v[66:67], v[206:207]
	v_pk_add_f32 v[68:69], v[68:69], v[208:209]
	v_lshlrev_b32_e32 v206, 16, v182
	v_and_b32_e32 v207, 0xffff0000, v182
	v_lshlrev_b32_e32 v208, 16, v183
	v_and_b32_e32 v209, 0xffff0000, v183
	v_pk_add_f32 v[58:59], v[58:59], v[206:207]
	v_pk_add_f32 v[60:61], v[60:61], v[208:209]
	global_load_dwordx4 v[176:179], v167, s[50:51] offset:192
	global_load_dwordx4 v[180:183], v167, s[10:11] offset:192
	v_cvt_pk_bf16_f32 v152, v66, v67
	v_cvt_pk_bf16_f32 v153, v68, v69
	v_cvt_pk_bf16_f32 v154, v58, v59
	v_cvt_pk_bf16_f32 v155, v60, v61
	s_nop 1
	v_permlane16_swap_b32_e32 v152, v154
	v_permlane16_swap_b32_e32 v153, v155
	global_store_dwordx4 v163, v[152:155], s[10:11]
	v_cvt_pk_bf16_f32 v156, v126, v127
	v_cvt_pk_bf16_f32 v157, v128, v129
	v_cvt_pk_bf16_f32 v158, v122, v123
	v_cvt_pk_bf16_f32 v159, v124, v125
	s_nop 1
	v_permlane16_swap_b32_e32 v156, v158
	v_permlane16_swap_b32_e32 v157, v159
	global_store_dwordx4 v160, v[156:159], s[10:11]
	v_cvt_pk_bf16_f32 v152, v118, v119
	v_cvt_pk_bf16_f32 v153, v120, v121
	v_cvt_pk_bf16_f32 v154, v114, v115
	v_cvt_pk_bf16_f32 v155, v116, v117
	s_nop 1
	v_permlane16_swap_b32_e32 v152, v154
	v_permlane16_swap_b32_e32 v153, v155
	global_store_dwordx4 v160, v[152:155], s[10:11] offset:64
	s_waitcnt vmcnt(15)
	v_permlane16_swap_b32_e32 v184, v186
	v_permlane16_swap_b32_e32 v185, v187
	v_permlane16_swap_b32_e32 v188, v190
	v_permlane16_swap_b32_e32 v189, v191
	v_lshlrev_b32_e32 v206, 16, v184
	v_and_b32_e32 v207, 0xffff0000, v184
	v_lshlrev_b32_e32 v208, 16, v185
	v_and_b32_e32 v209, 0xffff0000, v185
	v_pk_mul_f32 v[54:55], v[54:55], v[206:207]
	v_pk_mul_f32 v[56:57], v[56:57], v[208:209]
	v_lshlrev_b32_e32 v206, 16, v186
	v_and_b32_e32 v207, 0xffff0000, v186
	v_lshlrev_b32_e32 v208, 16, v187
	v_and_b32_e32 v209, 0xffff0000, v187
	v_pk_mul_f32 v[50:51], v[50:51], v[206:207]
	v_pk_mul_f32 v[52:53], v[52:53], v[208:209]
	v_lshlrev_b32_e32 v206, 16, v188
	v_and_b32_e32 v207, 0xffff0000, v188
	v_lshlrev_b32_e32 v208, 16, v189
	v_and_b32_e32 v209, 0xffff0000, v189
	v_pk_add_f32 v[54:55], v[54:55], v[206:207]
	v_pk_add_f32 v[56:57], v[56:57], v[208:209]
	v_lshlrev_b32_e32 v206, 16, v190
	v_and_b32_e32 v207, 0xffff0000, v190
	v_lshlrev_b32_e32 v208, 16, v191
	v_and_b32_e32 v209, 0xffff0000, v191
	v_pk_add_f32 v[50:51], v[50:51], v[206:207]
	v_pk_add_f32 v[52:53], v[52:53], v[208:209]
	v_cvt_pk_bf16_f32 v156, v54, v55
	v_cvt_pk_bf16_f32 v157, v56, v57
	v_cvt_pk_bf16_f32 v158, v50, v51
	v_cvt_pk_bf16_f32 v159, v52, v53
	s_nop 1
	v_permlane16_swap_b32_e32 v156, v158
	v_permlane16_swap_b32_e32 v157, v159
	global_store_dwordx4 v163, v[156:159], s[10:11] offset:64
	v_cvt_pk_bf16_f32 v152, v110, v111
	v_cvt_pk_bf16_f32 v153, v112, v113
	v_cvt_pk_bf16_f32 v154, v106, v107
	v_cvt_pk_bf16_f32 v155, v108, v109
	s_nop 1
	v_permlane16_swap_b32_e32 v152, v154
	v_permlane16_swap_b32_e32 v153, v155
	global_store_dwordx4 v160, v[152:155], s[10:11] offset:128
	s_waitcnt vmcnt(15)
; DI unsigned pk2(float lo, float hi) { f32x2 v = {lo, hi}; bf16x2_t b = __builtin_convertvector(v, bf16x2_t); return __builtin_bit_cast(unsigned, b); }
; DI float bflo(unsigned u) { return __uint_as_float(u << 16); }
; DI float bfhi(unsigned u) { return __uint_as_float(u & 0xffff0000u); }
; DI void phaseD(const Params& p0, const Slot sl, int layer, unsigned char* lds) {
;     ...
; #pragma unroll
;       for (int j = 0; j < 4; ++j) {
;         const long tok = (long)mt * 256 + wb * 64 + j * 16 + qi;
; #pragma unroll
;         for (int i = 0; i < 8; ++i) {
;           const long off = tok * 1024 + nt * 256 + wa * 128 + i * 16 + quad * 4;
;           const u32x2 xg = *(const u32x2*)(Gg + off);
;           const f32x4 v = acc[i][j];
;           float o0 = bflo(xg[0]) * v[0], o1 = bfhi(xg[0]) * v[1], o2 = bflo(xg[1]) * v[2], o3 = bfhi(xg[1]) * v[3];
;           if (which) { const u32x2 a = *(const u32x2*)(p.merged() + off); o0 += bflo(a[0]); o1 += bfhi(a[0]); o2 += bflo(a[1]); o3 += bfhi(a[1]); }
;           *(u32x2*)(p.merged() + off) = (u32x2){pk2(o0, o1), pk2(o2, o3)};
;           if ((i & 3) == 3) asm volatile("" ::: "memory");
;         }
;       }
	v_permlane16_swap_b32_e32 v192, v194
	v_permlane16_swap_b32_e32 v193, v195
	v_permlane16_swap_b32_e32 v196, v198
	v_permlane16_swap_b32_e32 v197, v199
	v_lshlrev_b32_e32 v206, 16, v192
	v_and_b32_e32 v207, 0xffff0000, v192
	v_lshlrev_b32_e32 v208, 16, v193
	v_and_b32_e32 v209, 0xffff0000, v193
	v_pk_mul_f32 v[46:47], v[46:47], v[206:207]
	v_pk_mul_f32 v[48:49], v[48:49], v[208:209]
	v_lshlrev_b32_e32 v206, 16, v194
	v_and_b32_e32 v207, 0xffff0000, v194
	v_lshlrev_b32_e32 v208, 16, v195
	v_and_b32_e32 v209, 0xffff0000, v195
	v_pk_mul_f32 v[42:43], v[42:43], v[206:207]
	v_pk_mul_f32 v[44:45], v[44:45], v[208:209]
	v_lshlrev_b32_e32 v206, 16, v196
	v_and_b32_e32 v207, 0xffff0000, v196
	v_lshlrev_b32_e32 v208, 16, v197
	v_and_b32_e32 v209, 0xffff0000, v197
	v_pk_add_f32 v[46:47], v[46:47], v[206:207]
	v_pk_add_f32 v[48:49], v[48:49], v[208:209]
	v_lshlrev_b32_e32 v206, 16, v198
	v_and_b32_e32 v207, 0xffff0000, v198
	v_lshlrev_b32_e32 v208, 16, v199
	v_and_b32_e32 v209, 0xffff0000, v199
	v_pk_add_f32 v[42:43], v[42:43], v[206:207]
	v_pk_add_f32 v[44:45], v[44:45], v[208:209]
	v_cvt_pk_bf16_f32 v156, v46, v47
	v_cvt_pk_bf16_f32 v157, v48, v49
	v_cvt_pk_bf16_f32 v158, v42, v43
	v_cvt_pk_bf16_f32 v159, v44, v45
	s_nop 1
	v_permlane16_swap_b32_e32 v156, v158
	v_permlane16_swap_b32_e32 v157, v159
	global_store_dwordx4 v163, v[156:159], s[10:11] offset:128
	v_cvt_pk_bf16_f32 v152, v102, v103
	v_cvt_pk_bf16_f32 v153, v104, v105
	v_cvt_pk_bf16_f32 v154, v98, v99
	v_cvt_pk_bf16_f32 v155, v100, v101
	s_nop 1
	v_permlane16_swap_b32_e32 v152, v154
	v_permlane16_swap_b32_e32 v153, v155
	global_store_dwordx4 v160, v[152:155], s[10:11] offset:192
	s_waitcnt vmcnt(15)
	v_permlane16_swap_b32_e32 v216, v218
	v_permlane16_swap_b32_e32 v217, v219
	v_permlane16_swap_b32_e32 v220, v222
	v_permlane16_swap_b32_e32 v221, v223
	v_lshlrev_b32_e32 v206, 16, v216
	v_and_b32_e32 v207, 0xffff0000, v216
	v_lshlrev_b32_e32 v208, 16, v217
	v_and_b32_e32 v209, 0xffff0000, v217
	v_pk_mul_f32 v[38:39], v[38:39], v[206:207]
	v_pk_mul_f32 v[40:41], v[40:41], v[208:209]
	v_lshlrev_b32_e32 v206, 16, v218
	v_and_b32_e32 v207, 0xffff0000, v218
	v_lshlrev_b32_e32 v208, 16, v219
	v_and_b32_e32 v209, 0xffff0000, v219
	v_pk_mul_f32 v[34:35], v[34:35], v[206:207]
	v_pk_mul_f32 v[36:37], v[36:37], v[208:209]
	v_lshlrev_b32_e32 v206, 16, v220
	v_and_b32_e32 v207, 0xffff0000, v220
	v_lshlrev_b32_e32 v208, 16, v221
	v_and_b32_e32 v209, 0xffff0000, v221
	v_pk_add_f32 v[38:39], v[38:39], v[206:207]
	v_pk_add_f32 v[40:41], v[40:41], v[208:209]
	v_lshlrev_b32_e32 v206, 16, v222
	v_and_b32_e32 v207, 0xffff0000, v222
	v_lshlrev_b32_e32 v208, 16, v223
	v_and_b32_e32 v209, 0xffff0000, v223
	v_pk_add_f32 v[34:35], v[34:35], v[206:207]
	v_pk_add_f32 v[36:37], v[36:37], v[208:209]
	v_cvt_pk_bf16_f32 v156, v38, v39
	v_cvt_pk_bf16_f32 v157, v40, v41
	v_cvt_pk_bf16_f32 v158, v34, v35
	v_cvt_pk_bf16_f32 v159, v36, v37
	s_nop 1
	v_permlane16_swap_b32_e32 v156, v158
	v_permlane16_swap_b32_e32 v157, v159
	global_store_dwordx4 v163, v[156:159], s[10:11] offset:192
	v_cvt_pk_bf16_f32 v152, v94, v95
	v_cvt_pk_bf16_f32 v153, v96, v97
	v_cvt_pk_bf16_f32 v154, v90, v91
	v_cvt_pk_bf16_f32 v155, v92, v93
	s_nop 1
	v_permlane16_swap_b32_e32 v152, v154
	v_permlane16_swap_b32_e32 v153, v155
	global_store_dwordx4 v161, v[152:155], s[10:11]
	s_waitcnt vmcnt(15)
	v_permlane16_swap_b32_e32 v224, v226
	v_permlane16_swap_b32_e32 v225, v227
	v_permlane16_swap_b32_e32 v240, v242
	v_permlane16_swap_b32_e32 v241, v243
	v_lshlrev_b32_e32 v206, 16, v224
	v_and_b32_e32 v207, 0xffff0000, v224
	v_lshlrev_b32_e32 v208, 16, v225
	v_and_b32_e32 v209, 0xffff0000, v225
	v_pk_mul_f32 v[30:31], v[30:31], v[206:207]
	v_pk_mul_f32 v[32:33], v[32:33], v[208:209]
	v_lshlrev_b32_e32 v206, 16, v226
	v_and_b32_e32 v207, 0xffff0000, v226
	v_lshlrev_b32_e32 v208, 16, v227
	v_and_b32_e32 v209, 0xffff0000, v227
	v_pk_mul_f32 v[26:27], v[26:27], v[206:207]
	v_pk_mul_f32 v[28:29], v[28:29], v[208:209]
	v_lshlrev_b32_e32 v206, 16, v240
	v_and_b32_e32 v207, 0xffff0000, v240
	v_lshlrev_b32_e32 v208, 16, v241
	v_and_b32_e32 v209, 0xffff0000, v241
	v_pk_add_f32 v[30:31], v[30:31], v[206:207]
	v_pk_add_f32 v[32:33], v[32:33], v[208:209]
	v_lshlrev_b32_e32 v206, 16, v242
	v_and_b32_e32 v207, 0xffff0000, v242
	v_lshlrev_b32_e32 v208, 16, v243
	v_and_b32_e32 v209, 0xffff0000, v243
	v_pk_add_f32 v[26:27], v[26:27], v[206:207]
	v_pk_add_f32 v[28:29], v[28:29], v[208:209]
	v_cvt_pk_bf16_f32 v156, v30, v31
	v_cvt_pk_bf16_f32 v157, v32, v33
	v_cvt_pk_bf16_f32 v158, v26, v27
	v_cvt_pk_bf16_f32 v159, v28, v29
	s_nop 1
	v_permlane16_swap_b32_e32 v156, v158
	v_permlane16_swap_b32_e32 v157, v159
	global_store_dwordx4 v167, v[156:159], s[10:11]
	v_cvt_pk_bf16_f32 v152, v86, v87
	v_cvt_pk_bf16_f32 v153, v88, v89
	v_cvt_pk_bf16_f32 v154, v82, v83
	v_cvt_pk_bf16_f32 v155, v84, v85
	s_nop 1
	v_permlane16_swap_b32_e32 v152, v154
	v_permlane16_swap_b32_e32 v153, v155
	global_store_dwordx4 v161, v[152:155], s[10:11] offset:64
	s_waitcnt vmcnt(15)
; DI unsigned pk2(float lo, float hi) { f32x2 v = {lo, hi}; bf16x2_t b = __builtin_convertvector(v, bf16x2_t); return __builtin_bit_cast(unsigned, b); }
; DI float bflo(unsigned u) { return __uint_as_float(u << 16); }
; DI float bfhi(unsigned u) { return __uint_as_float(u & 0xffff0000u); }
; DI void phaseD(const Params& p0, const Slot sl, int layer, unsigned char* lds) {
;     ...
; #pragma unroll
;       for (int j = 0; j < 4; ++j) {
;         const long tok = (long)mt * 256 + wb * 64 + j * 16 + qi;
; #pragma unroll
;         for (int i = 0; i < 8; ++i) {
;           const long off = tok * 1024 + nt * 256 + wa * 128 + i * 16 + quad * 4;
;           const u32x2 xg = *(const u32x2*)(Gg + off);
;           const f32x4 v = acc[i][j];
;           float o0 = bflo(xg[0]) * v[0], o1 = bfhi(xg[0]) * v[1], o2 = bflo(xg[1]) * v[2], o3 = bfhi(xg[1]) * v[3];
;           if (which) { const u32x2 a = *(const u32x2*)(p.merged() + off); o0 += bflo(a[0]); o1 += bfhi(a[0]); o2 += bflo(a[1]); o3 += bfhi(a[1]); }
;           *(u32x2*)(p.merged() + off) = (u32x2){pk2(o0, o1), pk2(o2, o3)};
;           if ((i & 3) == 3) asm volatile("" ::: "memory");
;         }
;       }
	v_permlane16_swap_b32_e32 v244, v246
	v_permlane16_swap_b32_e32 v245, v247
	v_permlane16_swap_b32_e32 v248, v250
	v_permlane16_swap_b32_e32 v249, v251
	v_lshlrev_b32_e32 v206, 16, v244
	v_and_b32_e32 v207, 0xffff0000, v244
	v_lshlrev_b32_e32 v208, 16, v245
	v_and_b32_e32 v209, 0xffff0000, v245
	v_pk_mul_f32 v[22:23], v[22:23], v[206:207]
	v_pk_mul_f32 v[24:25], v[24:25], v[208:209]
	v_lshlrev_b32_e32 v206, 16, v246
	v_and_b32_e32 v207, 0xffff0000, v246
	v_lshlrev_b32_e32 v208, 16, v247
	v_and_b32_e32 v209, 0xffff0000, v247
	v_pk_mul_f32 v[18:19], v[18:19], v[206:207]
	v_pk_mul_f32 v[20:21], v[20:21], v[208:209]
	v_lshlrev_b32_e32 v206, 16, v248
	v_and_b32_e32 v207, 0xffff0000, v248
	v_lshlrev_b32_e32 v208, 16, v249
	v_and_b32_e32 v209, 0xffff0000, v249
	v_pk_add_f32 v[22:23], v[22:23], v[206:207]
	v_pk_add_f32 v[24:25], v[24:25], v[208:209]
	v_lshlrev_b32_e32 v206, 16, v250
	v_and_b32_e32 v207, 0xffff0000, v250
	v_lshlrev_b32_e32 v208, 16, v251
	v_and_b32_e32 v209, 0xffff0000, v251
	v_pk_add_f32 v[18:19], v[18:19], v[206:207]
	v_pk_add_f32 v[20:21], v[20:21], v[208:209]
	v_cvt_pk_bf16_f32 v156, v22, v23
	v_cvt_pk_bf16_f32 v157, v24, v25
	v_cvt_pk_bf16_f32 v158, v18, v19
	v_cvt_pk_bf16_f32 v159, v20, v21
	s_nop 1
	v_permlane16_swap_b32_e32 v156, v158
	v_permlane16_swap_b32_e32 v157, v159
	global_store_dwordx4 v167, v[156:159], s[10:11] offset:64
	v_cvt_pk_bf16_f32 v152, v78, v79
	v_cvt_pk_bf16_f32 v153, v80, v81
	v_cvt_pk_bf16_f32 v154, v74, v75
	v_cvt_pk_bf16_f32 v155, v76, v77
	s_nop 1
	v_permlane16_swap_b32_e32 v152, v154
	v_permlane16_swap_b32_e32 v153, v155
	global_store_dwordx4 v161, v[152:155], s[10:11] offset:128
	s_waitcnt vmcnt(15)
	v_permlane16_swap_b32_e32 v168, v170
	v_permlane16_swap_b32_e32 v169, v171
	v_permlane16_swap_b32_e32 v172, v174
	v_permlane16_swap_b32_e32 v173, v175
	v_lshlrev_b32_e32 v206, 16, v168
	v_and_b32_e32 v207, 0xffff0000, v168
	v_lshlrev_b32_e32 v208, 16, v169
	v_and_b32_e32 v209, 0xffff0000, v169
	v_pk_mul_f32 v[14:15], v[14:15], v[206:207]
	v_pk_mul_f32 v[16:17], v[16:17], v[208:209]
	v_lshlrev_b32_e32 v206, 16, v170
	v_and_b32_e32 v207, 0xffff0000, v170
	v_lshlrev_b32_e32 v208, 16, v171
	v_and_b32_e32 v209, 0xffff0000, v171
	v_pk_mul_f32 v[10:11], v[10:11], v[206:207]
	v_pk_mul_f32 v[12:13], v[12:13], v[208:209]
	v_lshlrev_b32_e32 v206, 16, v172
	v_and_b32_e32 v207, 0xffff0000, v172
	v_lshlrev_b32_e32 v208, 16, v173
	v_and_b32_e32 v209, 0xffff0000, v173
	v_pk_add_f32 v[14:15], v[14:15], v[206:207]
	v_pk_add_f32 v[16:17], v[16:17], v[208:209]
	v_lshlrev_b32_e32 v206, 16, v174
	v_and_b32_e32 v207, 0xffff0000, v174
	v_lshlrev_b32_e32 v208, 16, v175
	v_and_b32_e32 v209, 0xffff0000, v175
	v_pk_add_f32 v[10:11], v[10:11], v[206:207]
	v_pk_add_f32 v[12:13], v[12:13], v[208:209]
	v_cvt_pk_bf16_f32 v156, v14, v15
	v_cvt_pk_bf16_f32 v157, v16, v17
	v_cvt_pk_bf16_f32 v158, v10, v11
	v_cvt_pk_bf16_f32 v159, v12, v13
	s_nop 1
	v_permlane16_swap_b32_e32 v156, v158
	v_permlane16_swap_b32_e32 v157, v159
	global_store_dwordx4 v167, v[156:159], s[10:11] offset:128
	v_cvt_pk_bf16_f32 v152, v70, v71
	v_cvt_pk_bf16_f32 v153, v72, v73
	v_cvt_pk_bf16_f32 v154, v62, v63
	v_cvt_pk_bf16_f32 v155, v64, v65
	s_nop 1
	v_permlane16_swap_b32_e32 v152, v154
	v_permlane16_swap_b32_e32 v153, v155
	global_store_dwordx4 v161, v[152:155], s[10:11] offset:192
	s_waitcnt vmcnt(15)
	v_permlane16_swap_b32_e32 v176, v178
	v_permlane16_swap_b32_e32 v177, v179
	v_permlane16_swap_b32_e32 v180, v182
	v_permlane16_swap_b32_e32 v181, v183
	v_lshlrev_b32_e32 v206, 16, v176
	v_and_b32_e32 v207, 0xffff0000, v176
	v_lshlrev_b32_e32 v208, 16, v177
	v_and_b32_e32 v209, 0xffff0000, v177
	v_pk_mul_f32 v[6:7], v[6:7], v[206:207]
	v_pk_mul_f32 v[8:9], v[8:9], v[208:209]
	v_lshlrev_b32_e32 v206, 16, v178
	v_and_b32_e32 v207, 0xffff0000, v178
	v_lshlrev_b32_e32 v208, 16, v179
	v_and_b32_e32 v209, 0xffff0000, v179
	v_pk_mul_f32 v[2:3], v[2:3], v[206:207]
	v_pk_mul_f32 v[4:5], v[4:5], v[208:209]
	v_lshlrev_b32_e32 v206, 16, v180
	v_and_b32_e32 v207, 0xffff0000, v180
	v_lshlrev_b32_e32 v208, 16, v181
	v_and_b32_e32 v209, 0xffff0000, v181
	v_pk_add_f32 v[6:7], v[6:7], v[206:207]
	v_pk_add_f32 v[8:9], v[8:9], v[208:209]
	v_lshlrev_b32_e32 v206, 16, v182
	v_and_b32_e32 v207, 0xffff0000, v182
	v_lshlrev_b32_e32 v208, 16, v183
	v_and_b32_e32 v209, 0xffff0000, v183
	v_pk_add_f32 v[2:3], v[2:3], v[206:207]
	v_pk_add_f32 v[4:5], v[4:5], v[208:209]
	v_cvt_pk_bf16_f32 v156, v6, v7
	v_cvt_pk_bf16_f32 v157, v8, v9
	v_cvt_pk_bf16_f32 v158, v2, v3
	v_cvt_pk_bf16_f32 v159, v4, v5
	s_nop 1
	v_permlane16_swap_b32_e32 v156, v158
	v_permlane16_swap_b32_e32 v157, v159
	global_store_dwordx4 v167, v[156:159], s[10:11] offset:192
	s_branch .Lmy_D_cont
